# GEMM: first K-loop iteration of each unit peeled with C=0 MFMAs; accumulator zeroing moves removed
# speedup vs baseline: 1.0061x; 1.0051x over previous
; #define PG8_STAGE(bufoff, gbase, voff) do { _Pragma("unroll") for (int _i = 0; _i < 2; ++_i) \
;         __builtin_amdgcn_global_load_lds((const unsigned*)((const char*)(gbase) + (voff)[_i]), (PG8_LAS unsigned*)(lds + (bufoff) + ldsw + _i * 8192), 16, 0, 0); } while (0)
; #define PG8_LDA(dst, b, h) do { _Pragma("unroll") for (int m = 0; m < 4; ++m) _Pragma("unroll") for (int k = 0; k < 2; ++k) dst[m][k] = *(const PG8_LAS bf16x8*)(lds + PG8_SA(b, h) + aoff + m * 2048 + k * 1024); } while (0)
; #define PG8_LDB(dst, b, h) do { _Pragma("unroll") for (int n = 0; n < 2; ++n) _Pragma("unroll") for (int k = 0; k < 2; ++k) dst[n][k] = *(const PG8_LAS bf16x8*)(lds + PG8_SB(b, h) + boff + n * 2048 + k * 1024); } while (0)
; #define PG8_WAIT_V(n) asm volatile("s_waitcnt vmcnt(" #n ")" ::: "memory")
; #define PG8_WAIT_L(n) asm volatile("s_waitcnt lgkmcnt(" #n ")" ::: "memory")
; #define PG8_BAR __builtin_amdgcn_s_barrier()
; #define PG8_SCHED __builtin_amdgcn_sched_barrier(0)
; template <class Epi, class Sched, bool ALIGN_EPI = false, bool SP2 = false>
; __device__ __forceinline__ void gemm_phase(PG8_LAS unsigned char* lds, const Gemm g, const Sched& S, const Epi& E) {
;     ...
;         const bool has_next = S.next(ui + 1, nxt);
;         const char* nA = has_next ? (const char*)g.A + (size_t)nxt.pm * tstep : cA; const char* nB = has_next ? (const char*)g.Bt + (size_t)nxt.pn * tstep : cB;
;         for (int t = 0; t < nt; t += 2) {
;             const bool last = (t == nt - 2);
;             const char* a1 = cA + (size_t)(t + 1) * kstep;
;             const char* a2 = last ? nA : cA + (size_t)(t + 2) * kstep; const char* b2 = last ? nB : cB + (size_t)(t + 2) * kstep;
;             const char* a3 = a2 + kstep; const char* b3 = b2 + kstep;
;             if (last && has_next) S.a_ready(nxt);
;             if constexpr (SP2) {
;             PG8_LDB(B0, 0, 0); PG8_LDB(B1, 0, 1); PG8_SCHED; PG8_LDA(At, 0, 0); PG8_STAGE(PG8_SA(1, 1), a1 + hstep, voffA);
;             PG8_WAIT_V(8); PG8_WAIT_L(0); PG8_BAR; PG8_MMA(0, 0, At, B0); PG8_MMA(0, 1, At, B1); PG8_BAR; PG8_SCHED;
;             PG8_LDA(At, 0, 1); PG8_STAGE(PG8_SB(0, 0), b2, voffB); PG8_STAGE(PG8_SB(0, 1), b2 + hstep, voffB); PG8_STAGE(PG8_SA(0, 0), a2, voffA);
;             PG8_WAIT_V(8); PG8_WAIT_L(0); PG8_BAR; PG8_MMA(1, 0, At, B0); PG8_MMA(1, 1, At, B1); PG8_BAR; PG8_SCHED;
.LBB0_264:
	s_ashr_i32 s73, s72, 31
	s_lshl_b64 s[52:53], s[72:73], 19
	s_add_u32 s74, s42, s52
	s_addc_u32 s75, s43, s53
	s_and_b64 s[52:53], s[4:5], exec
	s_cselect_b32 s73, s75, s1
	s_cselect_b32 s84, s74, s0
	s_ashr_i32 s71, s70, 31
	s_lshl_b64 s[52:53], s[70:71], 19
	s_add_u32 s76, s24, s52
	s_addc_u32 s77, s25, s53
	s_and_b64 s[52:53], s[4:5], exec
	s_cselect_b32 s52, s77, s7
	s_cselect_b32 s53, s76, s6
	s_add_u32 s0, s0, 0x40080
	s_addc_u32 s1, s1, 0
	s_add_u32 s71, s6, 0x100
	s_addc_u32 s54, s7, 0
	s_mov_b32 s55, -2
	s_waitcnt vmcnt(0)
	s_add_u32 s6, s0, 0xfffc0080
	s_addc_u32 s7, s1, -1
	s_add_i32 s50, 0, 0x10000
	s_cmp_eq_u32 s55, 12
	s_cselect_b32 s79, s73, s7
	s_cselect_b32 s78, s84, s6
	v_add_u32_e32 v0, s50, v177
	s_cselect_b32 s7, s52, s54
	s_cselect_b32 s6, s53, s71
	s_add_i32 s51, 0, 0x14000
	ds_read_b128 v[130:133], v0
	ds_read_b128 v[134:137], v0 offset:1024
	ds_read_b128 v[138:141], v0 offset:2048
	ds_read_b128 v[142:145], v0 offset:3072
	v_add_u32_e32 v0, s51, v177
	ds_read_b128 v[146:149], v0
	ds_read_b128 v[150:153], v0 offset:1024
	ds_read_b128 v[154:157], v0 offset:2048
	ds_read_b128 v[172:175], v0 offset:3072
	v_lshl_add_u64 v[184:185], s[0:1], 0, v[168:169]
	s_add_i32 m0, s62, 0xc000
	ds_read_b128 v[180:183], v179
	ds_read_b128 v[192:195], v179 offset:1024
	ds_read_b128 v[196:199], v179 offset:2048
	ds_read_b128 v[200:203], v179 offset:3072
	ds_read_b128 v[204:207], v179 offset:4096
	ds_read_b128 v[208:211], v179 offset:5120
	ds_read_b128 v[212:215], v179 offset:6144
	ds_read_b128 v[216:219], v179 offset:7168
	global_load_lds_dwordx4 v[184:185], off
	v_lshl_add_u64 v[184:185], s[0:1], 0, v[170:171]
	s_add_i32 m0, s62, 0xe000
	s_nop 0
	global_load_lds_dwordx4 v[184:185], off
	s_cmp_lg_u32 s100, 0
	s_cbranch_scc1 .Lpe_skipP_inproj_0
	s_waitcnt vmcnt(8)
.Lpe_skipP_inproj_0:
	s_waitcnt lgkmcnt(0)
	s_barrier
	s_setprio 1
	s_waitcnt lgkmcnt(0)
	v_mfma_f32_16x16x32_bf16 v[126:129], v[130:133], v[180:183], 0
	v_mfma_f32_16x16x32_bf16 v[94:97], v[138:141], v[180:183], 0
	v_mfma_f32_16x16x32_bf16 v[122:125], v[130:133], v[196:199], 0
	v_mfma_f32_16x16x32_bf16 v[90:93], v[138:141], v[196:199], 0
	v_mfma_f32_16x16x32_bf16 v[118:121], v[130:133], v[204:207], 0
	v_mfma_f32_16x16x32_bf16 v[86:89], v[138:141], v[204:207], 0
	v_mfma_f32_16x16x32_bf16 v[114:117], v[130:133], v[212:215], 0
	v_mfma_f32_16x16x32_bf16 v[82:85], v[138:141], v[212:215], 0
	v_mfma_f32_16x16x32_bf16 v[126:129], v[134:137], v[192:195], v[126:129]
	v_mfma_f32_16x16x32_bf16 v[94:97], v[142:145], v[192:195], v[94:97]
	v_mfma_f32_16x16x32_bf16 v[122:125], v[134:137], v[200:203], v[122:125]
	v_mfma_f32_16x16x32_bf16 v[90:93], v[142:145], v[200:203], v[90:93]
	v_mfma_f32_16x16x32_bf16 v[118:121], v[134:137], v[208:211], v[118:121]
	v_mfma_f32_16x16x32_bf16 v[86:89], v[142:145], v[208:211], v[86:89]
	v_mfma_f32_16x16x32_bf16 v[114:117], v[134:137], v[216:219], v[114:117]
	v_mfma_f32_16x16x32_bf16 v[82:85], v[142:145], v[216:219], v[82:85]
	s_setprio 0
	s_setprio 1
	v_mfma_f32_16x16x32_bf16 v[62:65], v[146:149], v[180:183], 0
	v_mfma_f32_16x16x32_bf16 v[30:33], v[154:157], v[180:183], 0
	v_mfma_f32_16x16x32_bf16 v[58:61], v[146:149], v[196:199], 0
	v_mfma_f32_16x16x32_bf16 v[26:29], v[154:157], v[196:199], 0
	v_mfma_f32_16x16x32_bf16 v[54:57], v[146:149], v[204:207], 0
	v_mfma_f32_16x16x32_bf16 v[22:25], v[154:157], v[204:207], 0
	v_mfma_f32_16x16x32_bf16 v[50:53], v[146:149], v[212:215], 0
	v_mfma_f32_16x16x32_bf16 v[18:21], v[154:157], v[212:215], 0
	v_mfma_f32_16x16x32_bf16 v[62:65], v[150:153], v[192:195], v[62:65]
	v_mfma_f32_16x16x32_bf16 v[30:33], v[172:175], v[192:195], v[30:33]
	v_mfma_f32_16x16x32_bf16 v[58:61], v[150:153], v[200:203], v[58:61]
	v_mfma_f32_16x16x32_bf16 v[26:29], v[172:175], v[200:203], v[26:29]
	v_mfma_f32_16x16x32_bf16 v[54:57], v[150:153], v[208:211], v[54:57]
	v_mfma_f32_16x16x32_bf16 v[22:25], v[172:175], v[208:211], v[22:25]
	v_mfma_f32_16x16x32_bf16 v[50:53], v[150:153], v[216:219], v[50:53]
	v_mfma_f32_16x16x32_bf16 v[18:21], v[172:175], v[216:219], v[18:21]
	s_setprio 0
	s_barrier
	s_add_i32 s50, s50, s35
	v_lshl_add_u64 v[184:185], s[6:7], 0, v[162:163]
	s_mov_b32 m0, s50
	ds_read_b128 v[180:183], v179 offset:16384
	ds_read_b128 v[192:195], v179 offset:17408
	ds_read_b128 v[196:199], v179 offset:18432
	ds_read_b128 v[200:203], v179 offset:19456
	ds_read_b128 v[204:207], v179 offset:20480
	ds_read_b128 v[208:211], v179 offset:21504
	ds_read_b128 v[212:215], v179 offset:22528
	ds_read_b128 v[216:219], v179 offset:23552
	global_load_lds_dwordx4 v[184:185], off
	s_add_i32 m0, s50, 0x2000
	s_add_u32 s56, s6, 0x40000
	v_lshl_add_u64 v[188:189], s[6:7], 0, v[158:159]
	s_addc_u32 s57, s7, 0
	s_add_i32 s50, s51, s35
	global_load_lds_dwordx4 v[188:189], off
	v_lshl_add_u64 v[190:191], s[56:57], 0, v[162:163]
	s_mov_b32 m0, s50
	v_lshl_add_u64 v[220:221], s[78:79], 0, v[160:161]
	global_load_lds_dwordx4 v[190:191], off
	v_lshl_add_u64 v[190:191], s[56:57], 0, v[158:159]
	s_add_i32 m0, s50, 0x2000
	s_nop 0
	global_load_lds_dwordx4 v[190:191], off
	v_lshl_add_u64 v[190:191], s[78:79], 0, v[164:165]
	s_mov_b32 m0, s62
	s_nop 0
	global_load_lds_dwordx4 v[190:191], off
	s_mov_b32 m0, s63
	s_nop 0
	global_load_lds_dwordx4 v[220:221], off
	s_cmp_lg_u32 s100, 0
	s_cbranch_scc1 .Lpe_skipP_inproj_1
	s_waitcnt vmcnt(8)
; #define PG8_STAGE(bufoff, gbase, voff) do { _Pragma("unroll") for (int _i = 0; _i < 2; ++_i) \
;         __builtin_amdgcn_global_load_lds((const unsigned*)((const char*)(gbase) + (voff)[_i]), (PG8_LAS unsigned*)(lds + (bufoff) + ldsw + _i * 8192), 16, 0, 0); } while (0)
; #define PG8_LDA(dst, b, h) do { _Pragma("unroll") for (int m = 0; m < 4; ++m) _Pragma("unroll") for (int k = 0; k < 2; ++k) dst[m][k] = *(const PG8_LAS bf16x8*)(lds + PG8_SA(b, h) + aoff + m * 2048 + k * 1024); } while (0)
; #define PG8_LDB(dst, b, h) do { _Pragma("unroll") for (int n = 0; n < 2; ++n) _Pragma("unroll") for (int k = 0; k < 2; ++k) dst[n][k] = *(const PG8_LAS bf16x8*)(lds + PG8_SB(b, h) + boff + n * 2048 + k * 1024); } while (0)
; #define PG8_MMA(ai, bj, At, Bt) do { __builtin_amdgcn_s_setprio(1); _Pragma("unroll") for (int m = 0; m < 4; ++m) _Pragma("unroll") for (int n = 0; n < 2; ++n) _Pragma("unroll") for (int k = 0; k < 2; ++k) \
;         acc[ai][bj][m][n] = __builtin_amdgcn_mfma_f32_16x16x32_bf16(Bt[n][k], At[m][k], acc[ai][bj][m][n], 0, 0, 0); __builtin_amdgcn_s_setprio(0); } while (0)
; #define PG8_WAIT_V(n) asm volatile("s_waitcnt vmcnt(" #n ")" ::: "memory")
; #define PG8_WAIT_L(n) asm volatile("s_waitcnt lgkmcnt(" #n ")" ::: "memory")
; #define PG8_BAR __builtin_amdgcn_s_barrier()
; #define PG8_SCHED __builtin_amdgcn_sched_barrier(0)
; template <class Epi, class Sched, bool ALIGN_EPI = false, bool SP2 = false>
; __device__ __forceinline__ void gemm_phase(PG8_LAS unsigned char* lds, const Gemm g, const Sched& S, const Epi& E) {
;     ...
;             PG8_WAIT_V(8); PG8_WAIT_L(0); PG8_BAR; PG8_MMA(1, 0, At, B0); PG8_MMA(1, 1, At, B1); PG8_BAR; PG8_SCHED;
;             PG8_LDB(B0, 1, 0); PG8_LDB(B1, 1, 1); PG8_SCHED; PG8_LDA(At, 1, 0); PG8_STAGE(PG8_SA(0, 1), a2 + hstep, voffA);
;             PG8_WAIT_V(8); PG8_WAIT_L(0); PG8_BAR; PG8_MMA(0, 0, At, B0); PG8_MMA(0, 1, At, B1); PG8_BAR; PG8_SCHED;
.Lpe_skipP_inproj_1:
	s_mov_b32 s100, 0
	s_waitcnt lgkmcnt(0)
	s_barrier
	s_setprio 1
	s_waitcnt lgkmcnt(0)
	v_mfma_f32_16x16x32_bf16 v[110:113], v[130:133], v[180:183], 0
	v_mfma_f32_16x16x32_bf16 v[78:81], v[138:141], v[180:183], 0
	v_mfma_f32_16x16x32_bf16 v[106:109], v[130:133], v[196:199], 0
	v_mfma_f32_16x16x32_bf16 v[74:77], v[138:141], v[196:199], 0
	v_mfma_f32_16x16x32_bf16 v[102:105], v[130:133], v[204:207], 0
	v_mfma_f32_16x16x32_bf16 v[70:73], v[138:141], v[204:207], 0
	v_mfma_f32_16x16x32_bf16 v[98:101], v[130:133], v[212:215], 0
	v_mfma_f32_16x16x32_bf16 v[66:69], v[138:141], v[212:215], 0
	v_mfma_f32_16x16x32_bf16 v[110:113], v[134:137], v[192:195], v[110:113]
	v_mfma_f32_16x16x32_bf16 v[78:81], v[142:145], v[192:195], v[78:81]
	v_mfma_f32_16x16x32_bf16 v[106:109], v[134:137], v[200:203], v[106:109]
	v_mfma_f32_16x16x32_bf16 v[74:77], v[142:145], v[200:203], v[74:77]
	v_mfma_f32_16x16x32_bf16 v[102:105], v[134:137], v[208:211], v[102:105]
	v_mfma_f32_16x16x32_bf16 v[70:73], v[142:145], v[208:211], v[70:73]
	v_mfma_f32_16x16x32_bf16 v[98:101], v[134:137], v[216:219], v[98:101]
	v_mfma_f32_16x16x32_bf16 v[66:69], v[142:145], v[216:219], v[66:69]
	s_setprio 0
	s_setprio 1
	v_mfma_f32_16x16x32_bf16 v[46:49], v[146:149], v[180:183], 0
	v_mfma_f32_16x16x32_bf16 v[14:17], v[154:157], v[180:183], 0
	v_mfma_f32_16x16x32_bf16 v[42:45], v[146:149], v[196:199], 0
	v_mfma_f32_16x16x32_bf16 v[10:13], v[154:157], v[196:199], 0
	v_mfma_f32_16x16x32_bf16 v[38:41], v[146:149], v[204:207], 0
	v_mfma_f32_16x16x32_bf16 v[6:9], v[154:157], v[204:207], 0
	v_mfma_f32_16x16x32_bf16 v[34:37], v[146:149], v[212:215], 0
	v_mfma_f32_16x16x32_bf16 v[2:5], v[154:157], v[212:215], 0
	v_mfma_f32_16x16x32_bf16 v[46:49], v[150:153], v[192:195], v[46:49]
	v_mfma_f32_16x16x32_bf16 v[14:17], v[172:175], v[192:195], v[14:17]
	v_mfma_f32_16x16x32_bf16 v[42:45], v[150:153], v[200:203], v[42:45]
	v_mfma_f32_16x16x32_bf16 v[10:13], v[172:175], v[200:203], v[10:13]
	v_mfma_f32_16x16x32_bf16 v[38:41], v[150:153], v[208:211], v[38:41]
	v_mfma_f32_16x16x32_bf16 v[6:9], v[172:175], v[208:211], v[6:9]
	v_mfma_f32_16x16x32_bf16 v[34:37], v[150:153], v[216:219], v[34:37]
	v_mfma_f32_16x16x32_bf16 v[2:5], v[172:175], v[216:219], v[2:5]
	s_setprio 0
	s_barrier
	s_add_i32 s50, 0, 0x18000
	v_add_u32_e32 v0, s50, v177
	s_add_i32 s51, 0, 0x1c000
	ds_read_b128 v[130:133], v0
	ds_read_b128 v[134:137], v0 offset:1024
	ds_read_b128 v[138:141], v0 offset:2048
	ds_read_b128 v[142:145], v0 offset:3072
	v_add_u32_e32 v0, s51, v177
	ds_read_b128 v[146:149], v0
	ds_read_b128 v[150:153], v0 offset:1024
	ds_read_b128 v[154:157], v0 offset:2048
	ds_read_b128 v[172:175], v0 offset:3072
	s_add_u32 s56, s78, 0x40000
	s_addc_u32 s57, s79, 0
	s_mov_b32 m0, s64
	v_lshl_add_u64 v[222:223], s[56:57], 0, v[164:165]
	ds_read_b128 v[180:183], v179 offset:32768
	ds_read_b128 v[192:195], v179 offset:33792
	ds_read_b128 v[196:199], v179 offset:34816
	ds_read_b128 v[200:203], v179 offset:35840
	ds_read_b128 v[204:207], v179 offset:36864
	ds_read_b128 v[208:211], v179 offset:37888
	ds_read_b128 v[212:215], v179 offset:38912
	ds_read_b128 v[216:219], v179 offset:39936
	global_load_lds_dwordx4 v[222:223], off
	v_lshl_add_u64 v[222:223], s[56:57], 0, v[160:161]
	s_mov_b32 m0, s80
	s_nop 0
	global_load_lds_dwordx4 v[222:223], off
	s_waitcnt vmcnt(8)
	s_waitcnt lgkmcnt(0)
	s_barrier
	s_setprio 1
	s_waitcnt lgkmcnt(0)
	v_mfma_f32_16x16x32_bf16 v[126:129], v[130:133], v[180:183], v[126:129]
	v_mfma_f32_16x16x32_bf16 v[94:97], v[138:141], v[180:183], v[94:97]
	v_mfma_f32_16x16x32_bf16 v[122:125], v[130:133], v[196:199], v[122:125]
	v_mfma_f32_16x16x32_bf16 v[90:93], v[138:141], v[196:199], v[90:93]
	v_mfma_f32_16x16x32_bf16 v[118:121], v[130:133], v[204:207], v[118:121]
	v_mfma_f32_16x16x32_bf16 v[86:89], v[138:141], v[204:207], v[86:89]
	v_mfma_f32_16x16x32_bf16 v[114:117], v[130:133], v[212:215], v[114:117]
	v_mfma_f32_16x16x32_bf16 v[82:85], v[138:141], v[212:215], v[82:85]
	v_mfma_f32_16x16x32_bf16 v[126:129], v[134:137], v[192:195], v[126:129]
	v_mfma_f32_16x16x32_bf16 v[94:97], v[142:145], v[192:195], v[94:97]
	v_mfma_f32_16x16x32_bf16 v[122:125], v[134:137], v[200:203], v[122:125]
	v_mfma_f32_16x16x32_bf16 v[90:93], v[142:145], v[200:203], v[90:93]
	v_mfma_f32_16x16x32_bf16 v[118:121], v[134:137], v[208:211], v[118:121]
	v_mfma_f32_16x16x32_bf16 v[86:89], v[142:145], v[208:211], v[86:89]
	v_mfma_f32_16x16x32_bf16 v[114:117], v[134:137], v[216:219], v[114:117]
	v_mfma_f32_16x16x32_bf16 v[82:85], v[142:145], v[216:219], v[82:85]
	s_setprio 0
	s_setprio 1
	v_mfma_f32_16x16x32_bf16 v[62:65], v[146:149], v[180:183], v[62:65]
	v_mfma_f32_16x16x32_bf16 v[30:33], v[154:157], v[180:183], v[30:33]
	v_mfma_f32_16x16x32_bf16 v[58:61], v[146:149], v[196:199], v[58:61]
	v_mfma_f32_16x16x32_bf16 v[26:29], v[154:157], v[196:199], v[26:29]
	v_mfma_f32_16x16x32_bf16 v[54:57], v[146:149], v[204:207], v[54:57]
	v_mfma_f32_16x16x32_bf16 v[22:25], v[154:157], v[204:207], v[22:25]
	v_mfma_f32_16x16x32_bf16 v[50:53], v[146:149], v[212:215], v[50:53]
	v_mfma_f32_16x16x32_bf16 v[18:21], v[154:157], v[212:215], v[18:21]
	v_mfma_f32_16x16x32_bf16 v[62:65], v[150:153], v[192:195], v[62:65]
	v_mfma_f32_16x16x32_bf16 v[30:33], v[172:175], v[192:195], v[30:33]
	v_mfma_f32_16x16x32_bf16 v[58:61], v[150:153], v[200:203], v[58:61]
	v_mfma_f32_16x16x32_bf16 v[26:29], v[172:175], v[200:203], v[26:29]
	v_mfma_f32_16x16x32_bf16 v[54:57], v[150:153], v[208:211], v[54:57]
	v_mfma_f32_16x16x32_bf16 v[22:25], v[172:175], v[208:211], v[22:25]
	v_mfma_f32_16x16x32_bf16 v[50:53], v[150:153], v[216:219], v[50:53]
	v_mfma_f32_16x16x32_bf16 v[18:21], v[172:175], v[216:219], v[18:21]
	s_setprio 0
	s_barrier
; #define PG8_STAGE(bufoff, gbase, voff) do { _Pragma("unroll") for (int _i = 0; _i < 2; ++_i) \
;         __builtin_amdgcn_global_load_lds((const unsigned*)((const char*)(gbase) + (voff)[_i]), (PG8_LAS unsigned*)(lds + (bufoff) + ldsw + _i * 8192), 16, 0, 0); } while (0)
; #define PG8_LDA(dst, b, h) do { _Pragma("unroll") for (int m = 0; m < 4; ++m) _Pragma("unroll") for (int k = 0; k < 2; ++k) dst[m][k] = *(const PG8_LAS bf16x8*)(lds + PG8_SA(b, h) + aoff + m * 2048 + k * 1024); } while (0)
; #define PG8_MMA(ai, bj, At, Bt) do { __builtin_amdgcn_s_setprio(1); _Pragma("unroll") for (int m = 0; m < 4; ++m) _Pragma("unroll") for (int n = 0; n < 2; ++n) _Pragma("unroll") for (int k = 0; k < 2; ++k) \
;         acc[ai][bj][m][n] = __builtin_amdgcn_mfma_f32_16x16x32_bf16(Bt[n][k], At[m][k], acc[ai][bj][m][n], 0, 0, 0); __builtin_amdgcn_s_setprio(0); } while (0)
; #define PG8_WAIT_V(n) asm volatile("s_waitcnt vmcnt(" #n ")" ::: "memory")
; #define PG8_WAIT_L(n) asm volatile("s_waitcnt lgkmcnt(" #n ")" ::: "memory")
; #define PG8_BAR __builtin_amdgcn_s_barrier()
; #define PG8_SCHED __builtin_amdgcn_sched_barrier(0)
; template <class Epi, class Sched, bool ALIGN_EPI = false, bool SP2 = false>
; __device__ __forceinline__ void gemm_phase(PG8_LAS unsigned char* lds, const Gemm g, const Sched& S, const Epi& E) {
;     ...
;             PG8_LDA(At, 1, 1); PG8_STAGE(PG8_SB(1, 0), b3, voffB); PG8_STAGE(PG8_SB(1, 1), b3 + hstep, voffB); PG8_STAGE(PG8_SA(1, 0), a3, voffA);
;             PG8_WAIT_V(8); PG8_WAIT_L(0); PG8_BAR; PG8_MMA(1, 0, At, B0); PG8_MMA(1, 1, At, B1); PG8_BAR; PG8_SCHED;
	s_add_i32 s50, s50, s35
	v_lshl_add_u64 v[184:185], v[184:185], 0, s[60:61]
	s_mov_b32 m0, s50
	ds_read_b128 v[180:183], v179 offset:49152
	ds_read_b128 v[192:195], v179 offset:50176
	ds_read_b128 v[196:199], v179 offset:51200
	ds_read_b128 v[200:203], v179 offset:52224
	ds_read_b128 v[204:207], v179 offset:53248
	ds_read_b128 v[208:211], v179 offset:54272
	ds_read_b128 v[212:215], v179 offset:55296
	ds_read_b128 v[216:219], v179 offset:56320
	global_load_lds_dwordx4 v[184:185], off
	s_add_i32 m0, s50, 0x2000
	s_add_u32 s6, s6, 0x40080
	v_lshl_add_u64 v[184:185], v[188:189], 0, s[60:61]
	s_addc_u32 s7, s7, 0
	s_add_i32 s50, s51, s35
	global_load_lds_dwordx4 v[184:185], off
	v_lshl_add_u64 v[184:185], s[6:7], 0, v[162:163]
	s_mov_b32 m0, s50
	s_nop 0
	global_load_lds_dwordx4 v[184:185], off
	v_lshl_add_u64 v[184:185], s[6:7], 0, v[158:159]
	s_add_i32 m0, s50, 0x2000
	s_nop 0
	global_load_lds_dwordx4 v[184:185], off
	v_lshl_add_u64 v[184:185], v[190:191], 0, s[60:61]
	s_mov_b32 m0, s81
	s_nop 0
	global_load_lds_dwordx4 v[184:185], off
	v_lshl_add_u64 v[184:185], v[220:221], 0, s[60:61]
	s_mov_b32 m0, s82
	s_nop 0
	global_load_lds_dwordx4 v[184:185], off
	s_waitcnt vmcnt(8)
	s_waitcnt lgkmcnt(0)
	s_barrier
	s_setprio 1
	s_waitcnt lgkmcnt(0)
	v_mfma_f32_16x16x32_bf16 v[110:113], v[130:133], v[180:183], v[110:113]
	v_mfma_f32_16x16x32_bf16 v[78:81], v[138:141], v[180:183], v[78:81]
	v_mfma_f32_16x16x32_bf16 v[106:109], v[130:133], v[196:199], v[106:109]
	v_mfma_f32_16x16x32_bf16 v[74:77], v[138:141], v[196:199], v[74:77]
	v_mfma_f32_16x16x32_bf16 v[102:105], v[130:133], v[204:207], v[102:105]
	v_mfma_f32_16x16x32_bf16 v[70:73], v[138:141], v[204:207], v[70:73]
	v_mfma_f32_16x16x32_bf16 v[98:101], v[130:133], v[212:215], v[98:101]
	v_mfma_f32_16x16x32_bf16 v[66:69], v[138:141], v[212:215], v[66:69]
	v_mfma_f32_16x16x32_bf16 v[110:113], v[134:137], v[192:195], v[110:113]
	v_mfma_f32_16x16x32_bf16 v[78:81], v[142:145], v[192:195], v[78:81]
	v_mfma_f32_16x16x32_bf16 v[106:109], v[134:137], v[200:203], v[106:109]
	v_mfma_f32_16x16x32_bf16 v[74:77], v[142:145], v[200:203], v[74:77]
	v_mfma_f32_16x16x32_bf16 v[102:105], v[134:137], v[208:211], v[102:105]
	v_mfma_f32_16x16x32_bf16 v[70:73], v[142:145], v[208:211], v[70:73]
	v_mfma_f32_16x16x32_bf16 v[98:101], v[134:137], v[216:219], v[98:101]
	v_mfma_f32_16x16x32_bf16 v[66:69], v[142:145], v[216:219], v[66:69]
	s_setprio 0
	s_setprio 1
	v_mfma_f32_16x16x32_bf16 v[46:49], v[146:149], v[180:183], v[46:49]
	v_mfma_f32_16x16x32_bf16 v[14:17], v[154:157], v[180:183], v[14:17]
	v_mfma_f32_16x16x32_bf16 v[42:45], v[146:149], v[196:199], v[42:45]
	v_mfma_f32_16x16x32_bf16 v[10:13], v[154:157], v[196:199], v[10:13]
	v_mfma_f32_16x16x32_bf16 v[38:41], v[146:149], v[204:207], v[38:41]
	v_mfma_f32_16x16x32_bf16 v[6:9], v[154:157], v[204:207], v[6:9]
	v_mfma_f32_16x16x32_bf16 v[34:37], v[146:149], v[212:215], v[34:37]
	v_mfma_f32_16x16x32_bf16 v[2:5], v[154:157], v[212:215], v[2:5]
	v_mfma_f32_16x16x32_bf16 v[46:49], v[150:153], v[192:195], v[46:49]
	v_mfma_f32_16x16x32_bf16 v[14:17], v[172:175], v[192:195], v[14:17]
	v_mfma_f32_16x16x32_bf16 v[42:45], v[150:153], v[200:203], v[42:45]
	v_mfma_f32_16x16x32_bf16 v[10:13], v[172:175], v[200:203], v[10:13]
	v_mfma_f32_16x16x32_bf16 v[38:41], v[150:153], v[208:211], v[38:41]
	v_mfma_f32_16x16x32_bf16 v[6:9], v[172:175], v[208:211], v[6:9]
	v_mfma_f32_16x16x32_bf16 v[34:37], v[150:153], v[216:219], v[34:37]
	v_mfma_f32_16x16x32_bf16 v[2:5], v[172:175], v[216:219], v[2:5]
	s_setprio 0
	s_barrier
	s_add_i32 s55, s55, 2
	s_add_u32 s0, s0, 0x100
	s_addc_u32 s1, s1, 0
	s_add_u32 s71, s71, 0x100
	s_addc_u32 s54, s54, 0
	s_cmp_gt_u32 s55, 13
	s_cbranch_scc0 .LBB0_265

; #define PG8_STAGE(bufoff, gbase, voff) do { _Pragma("unroll") for (int _i = 0; _i < 2; ++_i) \
;         __builtin_amdgcn_global_load_lds((const unsigned*)((const char*)(gbase) + (voff)[_i]), (PG8_LAS unsigned*)(lds + (bufoff) + ldsw + _i * 8192), 16, 0, 0); } while (0)
; #define PG8_LDA(dst, b, h) do { _Pragma("unroll") for (int m = 0; m < 4; ++m) _Pragma("unroll") for (int k = 0; k < 2; ++k) dst[m][k] = *(const PG8_LAS bf16x8*)(lds + PG8_SA(b, h) + aoff + m * 2048 + k * 1024); } while (0)
; #define PG8_LDB(dst, b, h) do { _Pragma("unroll") for (int n = 0; n < 2; ++n) _Pragma("unroll") for (int k = 0; k < 2; ++k) dst[n][k] = *(const PG8_LAS bf16x8*)(lds + PG8_SB(b, h) + boff + n * 2048 + k * 1024); } while (0)
; #define PG8_WAIT_V(n) asm volatile("s_waitcnt vmcnt(" #n ")" ::: "memory")
; #define PG8_WAIT_L(n) asm volatile("s_waitcnt lgkmcnt(" #n ")" ::: "memory")
; #define PG8_BAR __builtin_amdgcn_s_barrier()
; #define PG8_SCHED __builtin_amdgcn_sched_barrier(0)
; template <class Epi, class Sched, bool ALIGN_EPI = false, bool SP2 = false>
; __device__ __forceinline__ void gemm_phase(PG8_LAS unsigned char* lds, const Gemm g, const Sched& S, const Epi& E) {
;     ...
;         const bool has_next = S.next(ui + 1, nxt);
;         const char* nA = has_next ? (const char*)g.A + (size_t)nxt.pm * tstep : cA; const char* nB = has_next ? (const char*)g.Bt + (size_t)nxt.pn * tstep : cB;
;         for (int t = 0; t < nt; t += 2) {
;             const bool last = (t == nt - 2);
;             const char* a1 = cA + (size_t)(t + 1) * kstep;
;             const char* a2 = last ? nA : cA + (size_t)(t + 2) * kstep; const char* b2 = last ? nB : cB + (size_t)(t + 2) * kstep;
;             const char* a3 = a2 + kstep; const char* b3 = b2 + kstep;
;             if (last && has_next) S.a_ready(nxt);
;             if constexpr (SP2) {
;             PG8_LDB(B0, 0, 0); PG8_LDB(B1, 0, 1); PG8_SCHED; PG8_LDA(At, 0, 0); PG8_STAGE(PG8_SA(1, 1), a1 + hstep, voffA);
;             PG8_WAIT_V(8); PG8_WAIT_L(0); PG8_BAR; PG8_MMA(0, 0, At, B0); PG8_MMA(0, 1, At, B1); PG8_BAR; PG8_SCHED;
;             PG8_LDA(At, 0, 1); PG8_STAGE(PG8_SB(0, 0), b2, voffB); PG8_STAGE(PG8_SB(0, 1), b2 + hstep, voffB); PG8_STAGE(PG8_SA(0, 0), a2, voffA);
;             PG8_WAIT_V(8); PG8_WAIT_L(0); PG8_BAR; PG8_MMA(1, 0, At, B0); PG8_MMA(1, 1, At, B1); PG8_BAR; PG8_SCHED;
.LBB0_1035:
	s_ashr_i32 s73, s72, 31
	s_lshl_b64 s[52:53], s[72:73], 19
	s_add_u32 s74, s2, s52
	s_addc_u32 s75, s3, s53
	s_and_b64 s[52:53], s[8:9], exec
	s_cselect_b32 s52, s75, s79
	s_cselect_b32 s53, s74, s78
	s_ashr_i32 s71, s70, 31
	s_lshl_b64 s[54:55], s[70:71], 19
	s_add_u32 s76, s24, s54
	s_addc_u32 s77, s25, s55
	s_and_b64 s[54:55], s[8:9], exec
	s_cselect_b32 s64, s77, s81
	s_cselect_b32 s71, s76, s80
	s_add_u32 s54, s80, 0x100
	s_addc_u32 s55, s81, 0
	s_mov_b32 s56, -2
	s_waitcnt lgkmcnt(0)
	s_waitcnt vmcnt(0)
	s_add_u32 s80, s78, 0x100
	s_addc_u32 s81, s79, 0
	s_add_i32 s50, 0, 0x10000
	s_cmp_eq_u32 s56, 12
	s_cselect_b32 s85, s52, s81
	s_cselect_b32 s84, s53, s80
	s_cselect_b32 s83, s64, s55
	s_cselect_b32 s82, s71, s54
	s_add_i32 s51, 0, 0x14000
	v_add_u32_e32 v148, s50, v173
	v_add_u32_e32 v164, s51, v173
	ds_read_b128 v[136:139], v148
	ds_read_b128 v[140:143], v148 offset:1024
	ds_read_b128 v[144:147], v148 offset:2048
	ds_read_b128 v[148:151], v148 offset:3072
	ds_read_b128 v[152:155], v164
	ds_read_b128 v[156:159], v164 offset:1024
	ds_read_b128 v[160:163], v164 offset:2048
	ds_read_b128 v[164:167], v164 offset:3072
	v_lshl_add_u64 v[184:185], s[78:79], 0, v[132:133]
	s_add_i32 m0, s62, 0xc000
	ds_read_b128 v[168:171], v175
	ds_read_b128 v[176:179], v175 offset:1024
	ds_read_b128 v[180:183], v175 offset:2048
	ds_read_b128 v[192:195], v175 offset:3072
	ds_read_b128 v[196:199], v175 offset:4096
	ds_read_b128 v[200:203], v175 offset:5120
	ds_read_b128 v[204:207], v175 offset:6144
	ds_read_b128 v[208:211], v175 offset:7168
	global_load_lds_dwordx4 v[184:185], off
	v_lshl_add_u64 v[184:185], s[78:79], 0, v[134:135]
	s_add_i32 m0, s62, 0xe000
	s_nop 0
	global_load_lds_dwordx4 v[184:185], off
	s_cmp_lg_u32 s100, 0
	s_cbranch_scc1 .Lpe_skipP_out_0
	s_waitcnt vmcnt(8)
.Lpe_skipP_out_0:
	s_waitcnt lgkmcnt(0)
	s_barrier
	s_setprio 1
	s_waitcnt lgkmcnt(0)
	v_mfma_f32_16x16x32_bf16 v[126:129], v[136:139], v[168:171], 0
	v_mfma_f32_16x16x32_bf16 v[122:125], v[144:147], v[168:171], 0
	v_mfma_f32_16x16x32_bf16 v[110:113], v[136:139], v[180:183], 0
	v_mfma_f32_16x16x32_bf16 v[106:109], v[144:147], v[180:183], 0
	v_mfma_f32_16x16x32_bf16 v[94:97], v[136:139], v[196:199], 0
	v_mfma_f32_16x16x32_bf16 v[90:93], v[144:147], v[196:199], 0
	v_mfma_f32_16x16x32_bf16 v[78:81], v[136:139], v[204:207], 0
	v_mfma_f32_16x16x32_bf16 v[74:77], v[144:147], v[204:207], 0
	v_mfma_f32_16x16x32_bf16 v[126:129], v[140:143], v[176:179], v[126:129]
	v_mfma_f32_16x16x32_bf16 v[122:125], v[148:151], v[176:179], v[122:125]
	v_mfma_f32_16x16x32_bf16 v[110:113], v[140:143], v[192:195], v[110:113]
	v_mfma_f32_16x16x32_bf16 v[106:109], v[148:151], v[192:195], v[106:109]
	v_mfma_f32_16x16x32_bf16 v[94:97], v[140:143], v[200:203], v[94:97]
	v_mfma_f32_16x16x32_bf16 v[90:93], v[148:151], v[200:203], v[90:93]
	v_mfma_f32_16x16x32_bf16 v[78:81], v[140:143], v[208:211], v[78:81]
	v_mfma_f32_16x16x32_bf16 v[74:77], v[148:151], v[208:211], v[74:77]
	s_setprio 0
	s_setprio 1
	v_mfma_f32_16x16x32_bf16 v[118:121], v[152:155], v[168:171], 0
	v_mfma_f32_16x16x32_bf16 v[114:117], v[160:163], v[168:171], 0
	v_mfma_f32_16x16x32_bf16 v[102:105], v[152:155], v[180:183], 0
	v_mfma_f32_16x16x32_bf16 v[98:101], v[160:163], v[180:183], 0
	v_mfma_f32_16x16x32_bf16 v[86:89], v[152:155], v[196:199], 0
	v_mfma_f32_16x16x32_bf16 v[82:85], v[160:163], v[196:199], 0
	v_mfma_f32_16x16x32_bf16 v[70:73], v[152:155], v[204:207], 0
	v_mfma_f32_16x16x32_bf16 v[66:69], v[160:163], v[204:207], 0
	v_mfma_f32_16x16x32_bf16 v[118:121], v[156:159], v[176:179], v[118:121]
	v_mfma_f32_16x16x32_bf16 v[114:117], v[164:167], v[176:179], v[114:117]
	v_mfma_f32_16x16x32_bf16 v[102:105], v[156:159], v[192:195], v[102:105]
	v_mfma_f32_16x16x32_bf16 v[98:101], v[164:167], v[192:195], v[98:101]
	v_mfma_f32_16x16x32_bf16 v[86:89], v[156:159], v[200:203], v[86:89]
	v_mfma_f32_16x16x32_bf16 v[82:85], v[164:167], v[200:203], v[82:85]
	v_mfma_f32_16x16x32_bf16 v[70:73], v[156:159], v[208:211], v[70:73]
	v_mfma_f32_16x16x32_bf16 v[66:69], v[164:167], v[208:211], v[66:69]
	s_setprio 0
	s_barrier
	s_add_i32 s50, s50, s35
	v_lshl_add_u64 v[184:185], s[82:83], 0, v[0:1]
	s_mov_b32 m0, s50
	ds_read_b128 v[168:171], v175 offset:16384
	ds_read_b128 v[176:179], v175 offset:17408
	ds_read_b128 v[180:183], v175 offset:18432
	ds_read_b128 v[192:195], v175 offset:19456
	ds_read_b128 v[196:199], v175 offset:20480
	ds_read_b128 v[200:203], v175 offset:21504
	ds_read_b128 v[204:207], v175 offset:22528
	ds_read_b128 v[208:211], v175 offset:23552
	global_load_lds_dwordx4 v[184:185], off
	s_add_i32 m0, s50, 0x2000
	s_add_u32 s78, s82, 0x40000
	v_lshl_add_u64 v[188:189], s[82:83], 0, v[130:131]
	s_addc_u32 s79, s83, 0
	s_add_i32 s50, s51, s35
	global_load_lds_dwordx4 v[188:189], off
	v_lshl_add_u64 v[190:191], s[78:79], 0, v[0:1]
	s_mov_b32 m0, s50
	v_lshl_add_u64 v[212:213], s[84:85], 0, v[130:131]
	global_load_lds_dwordx4 v[190:191], off
	v_lshl_add_u64 v[190:191], s[78:79], 0, v[130:131]
	s_add_i32 m0, s50, 0x2000
	s_nop 0
	global_load_lds_dwordx4 v[190:191], off
	v_lshl_add_u64 v[190:191], s[84:85], 0, v[0:1]
	s_mov_b32 m0, s62
	s_nop 0
	global_load_lds_dwordx4 v[190:191], off
	s_mov_b32 m0, s63
	s_nop 0
	global_load_lds_dwordx4 v[212:213], off
	s_cmp_lg_u32 s100, 0
	s_cbranch_scc1 .Lpe_skipP_out_1
	s_waitcnt vmcnt(8)
; #define PG8_STAGE(bufoff, gbase, voff) do { _Pragma("unroll") for (int _i = 0; _i < 2; ++_i) \
;         __builtin_amdgcn_global_load_lds((const unsigned*)((const char*)(gbase) + (voff)[_i]), (PG8_LAS unsigned*)(lds + (bufoff) + ldsw + _i * 8192), 16, 0, 0); } while (0)
; #define PG8_LDA(dst, b, h) do { _Pragma("unroll") for (int m = 0; m < 4; ++m) _Pragma("unroll") for (int k = 0; k < 2; ++k) dst[m][k] = *(const PG8_LAS bf16x8*)(lds + PG8_SA(b, h) + aoff + m * 2048 + k * 1024); } while (0)
; #define PG8_LDB(dst, b, h) do { _Pragma("unroll") for (int n = 0; n < 2; ++n) _Pragma("unroll") for (int k = 0; k < 2; ++k) dst[n][k] = *(const PG8_LAS bf16x8*)(lds + PG8_SB(b, h) + boff + n * 2048 + k * 1024); } while (0)
; #define PG8_MMA(ai, bj, At, Bt) do { __builtin_amdgcn_s_setprio(1); _Pragma("unroll") for (int m = 0; m < 4; ++m) _Pragma("unroll") for (int n = 0; n < 2; ++n) _Pragma("unroll") for (int k = 0; k < 2; ++k) \
;         acc[ai][bj][m][n] = __builtin_amdgcn_mfma_f32_16x16x32_bf16(Bt[n][k], At[m][k], acc[ai][bj][m][n], 0, 0, 0); __builtin_amdgcn_s_setprio(0); } while (0)
; #define PG8_WAIT_V(n) asm volatile("s_waitcnt vmcnt(" #n ")" ::: "memory")
; #define PG8_WAIT_L(n) asm volatile("s_waitcnt lgkmcnt(" #n ")" ::: "memory")
; #define PG8_BAR __builtin_amdgcn_s_barrier()
; #define PG8_SCHED __builtin_amdgcn_sched_barrier(0)
; template <class Epi, class Sched, bool ALIGN_EPI = false, bool SP2 = false>
; __device__ __forceinline__ void gemm_phase(PG8_LAS unsigned char* lds, const Gemm g, const Sched& S, const Epi& E) {
;     ...
;             PG8_WAIT_V(8); PG8_WAIT_L(0); PG8_BAR; PG8_MMA(1, 0, At, B0); PG8_MMA(1, 1, At, B1); PG8_BAR; PG8_SCHED;
;             PG8_LDB(B0, 1, 0); PG8_LDB(B1, 1, 1); PG8_SCHED; PG8_LDA(At, 1, 0); PG8_STAGE(PG8_SA(0, 1), a2 + hstep, voffA);
;             PG8_WAIT_V(8); PG8_WAIT_L(0); PG8_BAR; PG8_MMA(0, 0, At, B0); PG8_MMA(0, 1, At, B1); PG8_BAR; PG8_SCHED;
.Lpe_skipP_out_1:
	s_mov_b32 s100, 0
	s_waitcnt lgkmcnt(0)
	s_barrier
	s_setprio 1
	s_waitcnt lgkmcnt(0)
	v_mfma_f32_16x16x32_bf16 v[62:65], v[136:139], v[168:171], 0
	v_mfma_f32_16x16x32_bf16 v[58:61], v[144:147], v[168:171], 0
	v_mfma_f32_16x16x32_bf16 v[46:49], v[136:139], v[180:183], 0
	v_mfma_f32_16x16x32_bf16 v[42:45], v[144:147], v[180:183], 0
	v_mfma_f32_16x16x32_bf16 v[30:33], v[136:139], v[196:199], 0
	v_mfma_f32_16x16x32_bf16 v[26:29], v[144:147], v[196:199], 0
	v_mfma_f32_16x16x32_bf16 v[14:17], v[136:139], v[204:207], 0
	v_mfma_f32_16x16x32_bf16 v[10:13], v[144:147], v[204:207], 0
	v_mfma_f32_16x16x32_bf16 v[62:65], v[140:143], v[176:179], v[62:65]
	v_mfma_f32_16x16x32_bf16 v[58:61], v[148:151], v[176:179], v[58:61]
	v_mfma_f32_16x16x32_bf16 v[46:49], v[140:143], v[192:195], v[46:49]
	v_mfma_f32_16x16x32_bf16 v[42:45], v[148:151], v[192:195], v[42:45]
	v_mfma_f32_16x16x32_bf16 v[30:33], v[140:143], v[200:203], v[30:33]
	v_mfma_f32_16x16x32_bf16 v[26:29], v[148:151], v[200:203], v[26:29]
	v_mfma_f32_16x16x32_bf16 v[14:17], v[140:143], v[208:211], v[14:17]
	v_mfma_f32_16x16x32_bf16 v[10:13], v[148:151], v[208:211], v[10:13]
	s_setprio 0
	s_setprio 1
	v_mfma_f32_16x16x32_bf16 v[54:57], v[152:155], v[168:171], 0
	v_mfma_f32_16x16x32_bf16 v[50:53], v[160:163], v[168:171], 0
	v_mfma_f32_16x16x32_bf16 v[38:41], v[152:155], v[180:183], 0
	v_mfma_f32_16x16x32_bf16 v[34:37], v[160:163], v[180:183], 0
	v_mfma_f32_16x16x32_bf16 v[22:25], v[152:155], v[196:199], 0
	v_mfma_f32_16x16x32_bf16 v[18:21], v[160:163], v[196:199], 0
	v_mfma_f32_16x16x32_bf16 v[6:9], v[152:155], v[204:207], 0
	v_mfma_f32_16x16x32_bf16 v[2:5], v[160:163], v[204:207], 0
	v_mfma_f32_16x16x32_bf16 v[54:57], v[156:159], v[176:179], v[54:57]
	v_mfma_f32_16x16x32_bf16 v[50:53], v[164:167], v[176:179], v[50:53]
	v_mfma_f32_16x16x32_bf16 v[38:41], v[156:159], v[192:195], v[38:41]
	v_mfma_f32_16x16x32_bf16 v[34:37], v[164:167], v[192:195], v[34:37]
	v_mfma_f32_16x16x32_bf16 v[22:25], v[156:159], v[200:203], v[22:25]
	v_mfma_f32_16x16x32_bf16 v[18:21], v[164:167], v[200:203], v[18:21]
	v_mfma_f32_16x16x32_bf16 v[6:9], v[156:159], v[208:211], v[6:9]
	v_mfma_f32_16x16x32_bf16 v[2:5], v[164:167], v[208:211], v[2:5]
	s_setprio 0
	s_barrier
	s_add_i32 s50, 0, 0x18000
	s_add_i32 s51, 0, 0x1c000
	v_add_u32_e32 v148, s50, v173
	v_add_u32_e32 v164, s51, v173
	ds_read_b128 v[136:139], v148
	ds_read_b128 v[140:143], v148 offset:1024
	ds_read_b128 v[144:147], v148 offset:2048
	ds_read_b128 v[148:151], v148 offset:3072
	ds_read_b128 v[152:155], v164
	ds_read_b128 v[156:159], v164 offset:1024
	ds_read_b128 v[160:163], v164 offset:2048
	ds_read_b128 v[164:167], v164 offset:3072
	s_add_u32 s78, s84, 0x40000
	s_addc_u32 s79, s85, 0
	s_mov_b32 m0, s86
	v_lshl_add_u64 v[214:215], s[78:79], 0, v[0:1]
	ds_read_b128 v[168:171], v175 offset:32768
	ds_read_b128 v[176:179], v175 offset:33792
	ds_read_b128 v[180:183], v175 offset:34816
	ds_read_b128 v[192:195], v175 offset:35840
	ds_read_b128 v[196:199], v175 offset:36864
	ds_read_b128 v[200:203], v175 offset:37888
	ds_read_b128 v[204:207], v175 offset:38912
	ds_read_b128 v[208:211], v175 offset:39936
	global_load_lds_dwordx4 v[214:215], off
	v_lshl_add_u64 v[214:215], s[78:79], 0, v[130:131]
	s_mov_b32 m0, s87
	s_nop 0
	global_load_lds_dwordx4 v[214:215], off
	s_waitcnt vmcnt(8)
	s_waitcnt lgkmcnt(0)
	s_barrier
	s_setprio 1
	s_waitcnt lgkmcnt(0)
	v_mfma_f32_16x16x32_bf16 v[126:129], v[136:139], v[168:171], v[126:129]
	v_mfma_f32_16x16x32_bf16 v[122:125], v[144:147], v[168:171], v[122:125]
	v_mfma_f32_16x16x32_bf16 v[110:113], v[136:139], v[180:183], v[110:113]
	v_mfma_f32_16x16x32_bf16 v[106:109], v[144:147], v[180:183], v[106:109]
	v_mfma_f32_16x16x32_bf16 v[94:97], v[136:139], v[196:199], v[94:97]
	v_mfma_f32_16x16x32_bf16 v[90:93], v[144:147], v[196:199], v[90:93]
	v_mfma_f32_16x16x32_bf16 v[78:81], v[136:139], v[204:207], v[78:81]
	v_mfma_f32_16x16x32_bf16 v[74:77], v[144:147], v[204:207], v[74:77]
	v_mfma_f32_16x16x32_bf16 v[126:129], v[140:143], v[176:179], v[126:129]
	v_mfma_f32_16x16x32_bf16 v[122:125], v[148:151], v[176:179], v[122:125]
	v_mfma_f32_16x16x32_bf16 v[110:113], v[140:143], v[192:195], v[110:113]
	v_mfma_f32_16x16x32_bf16 v[106:109], v[148:151], v[192:195], v[106:109]
	v_mfma_f32_16x16x32_bf16 v[94:97], v[140:143], v[200:203], v[94:97]
	v_mfma_f32_16x16x32_bf16 v[90:93], v[148:151], v[200:203], v[90:93]
	v_mfma_f32_16x16x32_bf16 v[78:81], v[140:143], v[208:211], v[78:81]
	v_mfma_f32_16x16x32_bf16 v[74:77], v[148:151], v[208:211], v[74:77]
	s_setprio 0
	s_setprio 1
	v_mfma_f32_16x16x32_bf16 v[118:121], v[152:155], v[168:171], v[118:121]
	v_mfma_f32_16x16x32_bf16 v[114:117], v[160:163], v[168:171], v[114:117]
	v_mfma_f32_16x16x32_bf16 v[102:105], v[152:155], v[180:183], v[102:105]
	v_mfma_f32_16x16x32_bf16 v[98:101], v[160:163], v[180:183], v[98:101]
	v_mfma_f32_16x16x32_bf16 v[86:89], v[152:155], v[196:199], v[86:89]
	v_mfma_f32_16x16x32_bf16 v[82:85], v[160:163], v[196:199], v[82:85]
	v_mfma_f32_16x16x32_bf16 v[70:73], v[152:155], v[204:207], v[70:73]
	v_mfma_f32_16x16x32_bf16 v[66:69], v[160:163], v[204:207], v[66:69]
	v_mfma_f32_16x16x32_bf16 v[118:121], v[156:159], v[176:179], v[118:121]
	v_mfma_f32_16x16x32_bf16 v[114:117], v[164:167], v[176:179], v[114:117]
	v_mfma_f32_16x16x32_bf16 v[102:105], v[156:159], v[192:195], v[102:105]
	v_mfma_f32_16x16x32_bf16 v[98:101], v[164:167], v[192:195], v[98:101]
	v_mfma_f32_16x16x32_bf16 v[86:89], v[156:159], v[200:203], v[86:89]
	v_mfma_f32_16x16x32_bf16 v[82:85], v[164:167], v[200:203], v[82:85]
	v_mfma_f32_16x16x32_bf16 v[70:73], v[156:159], v[208:211], v[70:73]
	v_mfma_f32_16x16x32_bf16 v[66:69], v[164:167], v[208:211], v[66:69]
	s_setprio 0
	s_barrier
; #define PG8_STAGE(bufoff, gbase, voff) do { _Pragma("unroll") for (int _i = 0; _i < 2; ++_i) \
;         __builtin_amdgcn_global_load_lds((const unsigned*)((const char*)(gbase) + (voff)[_i]), (PG8_LAS unsigned*)(lds + (bufoff) + ldsw + _i * 8192), 16, 0, 0); } while (0)
; #define PG8_LDA(dst, b, h) do { _Pragma("unroll") for (int m = 0; m < 4; ++m) _Pragma("unroll") for (int k = 0; k < 2; ++k) dst[m][k] = *(const PG8_LAS bf16x8*)(lds + PG8_SA(b, h) + aoff + m * 2048 + k * 1024); } while (0)
; #define PG8_MMA(ai, bj, At, Bt) do { __builtin_amdgcn_s_setprio(1); _Pragma("unroll") for (int m = 0; m < 4; ++m) _Pragma("unroll") for (int n = 0; n < 2; ++n) _Pragma("unroll") for (int k = 0; k < 2; ++k) \
;         acc[ai][bj][m][n] = __builtin_amdgcn_mfma_f32_16x16x32_bf16(Bt[n][k], At[m][k], acc[ai][bj][m][n], 0, 0, 0); __builtin_amdgcn_s_setprio(0); } while (0)
; #define PG8_WAIT_V(n) asm volatile("s_waitcnt vmcnt(" #n ")" ::: "memory")
; #define PG8_WAIT_L(n) asm volatile("s_waitcnt lgkmcnt(" #n ")" ::: "memory")
; #define PG8_BAR __builtin_amdgcn_s_barrier()
; #define PG8_SCHED __builtin_amdgcn_sched_barrier(0)
; template <class Epi, class Sched, bool ALIGN_EPI = false, bool SP2 = false>
; __device__ __forceinline__ void gemm_phase(PG8_LAS unsigned char* lds, const Gemm g, const Sched& S, const Epi& E) {
;     ...
;             PG8_LDA(At, 1, 1); PG8_STAGE(PG8_SB(1, 0), b3, voffB); PG8_STAGE(PG8_SB(1, 1), b3 + hstep, voffB); PG8_STAGE(PG8_SA(1, 0), a3, voffA);
;             PG8_WAIT_V(8); PG8_WAIT_L(0); PG8_BAR; PG8_MMA(1, 0, At, B0); PG8_MMA(1, 1, At, B1); PG8_BAR; PG8_SCHED;
	s_add_i32 s50, s50, s35
	v_lshl_add_u64 v[184:185], v[184:185], 0, s[60:61]
	s_mov_b32 m0, s50
	ds_read_b128 v[168:171], v175 offset:49152
	ds_read_b128 v[176:179], v175 offset:50176
	ds_read_b128 v[180:183], v175 offset:51200
	ds_read_b128 v[192:195], v175 offset:52224
	ds_read_b128 v[196:199], v175 offset:53248
	ds_read_b128 v[200:203], v175 offset:54272
	ds_read_b128 v[204:207], v175 offset:55296
	ds_read_b128 v[208:211], v175 offset:56320
	global_load_lds_dwordx4 v[184:185], off
	s_add_i32 m0, s50, 0x2000
	s_add_u32 s78, s82, 0x40080
	v_lshl_add_u64 v[184:185], v[188:189], 0, s[60:61]
	s_addc_u32 s79, s83, 0
	s_add_i32 s50, s51, s35
	global_load_lds_dwordx4 v[184:185], off
	v_lshl_add_u64 v[184:185], s[78:79], 0, v[0:1]
	s_mov_b32 m0, s50
	s_nop 0
	global_load_lds_dwordx4 v[184:185], off
	v_lshl_add_u64 v[184:185], s[78:79], 0, v[130:131]
	s_add_i32 m0, s50, 0x2000
	s_nop 0
	global_load_lds_dwordx4 v[184:185], off
	v_lshl_add_u64 v[184:185], v[190:191], 0, s[60:61]
	s_mov_b32 m0, s94
	s_nop 0
	global_load_lds_dwordx4 v[184:185], off
	v_lshl_add_u64 v[184:185], v[212:213], 0, s[60:61]
	s_mov_b32 m0, s95
	s_nop 0
	global_load_lds_dwordx4 v[184:185], off
	s_waitcnt vmcnt(8)
	s_waitcnt lgkmcnt(0)
	s_barrier
	s_setprio 1
	s_waitcnt lgkmcnt(0)
	v_mfma_f32_16x16x32_bf16 v[62:65], v[136:139], v[168:171], v[62:65]
	v_mfma_f32_16x16x32_bf16 v[58:61], v[144:147], v[168:171], v[58:61]
	v_mfma_f32_16x16x32_bf16 v[46:49], v[136:139], v[180:183], v[46:49]
	v_mfma_f32_16x16x32_bf16 v[42:45], v[144:147], v[180:183], v[42:45]
	v_mfma_f32_16x16x32_bf16 v[30:33], v[136:139], v[196:199], v[30:33]
	v_mfma_f32_16x16x32_bf16 v[26:29], v[144:147], v[196:199], v[26:29]
	v_mfma_f32_16x16x32_bf16 v[14:17], v[136:139], v[204:207], v[14:17]
	v_mfma_f32_16x16x32_bf16 v[10:13], v[144:147], v[204:207], v[10:13]
	v_mfma_f32_16x16x32_bf16 v[62:65], v[140:143], v[176:179], v[62:65]
	v_mfma_f32_16x16x32_bf16 v[58:61], v[148:151], v[176:179], v[58:61]
	v_mfma_f32_16x16x32_bf16 v[46:49], v[140:143], v[192:195], v[46:49]
	v_mfma_f32_16x16x32_bf16 v[42:45], v[148:151], v[192:195], v[42:45]
	v_mfma_f32_16x16x32_bf16 v[30:33], v[140:143], v[200:203], v[30:33]
	v_mfma_f32_16x16x32_bf16 v[26:29], v[148:151], v[200:203], v[26:29]
	v_mfma_f32_16x16x32_bf16 v[14:17], v[140:143], v[208:211], v[14:17]
	v_mfma_f32_16x16x32_bf16 v[10:13], v[148:151], v[208:211], v[10:13]
	s_setprio 0
	s_setprio 1
	v_mfma_f32_16x16x32_bf16 v[54:57], v[152:155], v[168:171], v[54:57]
	v_mfma_f32_16x16x32_bf16 v[50:53], v[160:163], v[168:171], v[50:53]
	v_mfma_f32_16x16x32_bf16 v[38:41], v[152:155], v[180:183], v[38:41]
	v_mfma_f32_16x16x32_bf16 v[34:37], v[160:163], v[180:183], v[34:37]
	v_mfma_f32_16x16x32_bf16 v[22:25], v[152:155], v[196:199], v[22:25]
	v_mfma_f32_16x16x32_bf16 v[18:21], v[160:163], v[196:199], v[18:21]
	v_mfma_f32_16x16x32_bf16 v[6:9], v[152:155], v[204:207], v[6:9]
	v_mfma_f32_16x16x32_bf16 v[2:5], v[160:163], v[204:207], v[2:5]
	v_mfma_f32_16x16x32_bf16 v[54:57], v[156:159], v[176:179], v[54:57]
	v_mfma_f32_16x16x32_bf16 v[50:53], v[164:167], v[176:179], v[50:53]
	v_mfma_f32_16x16x32_bf16 v[38:41], v[156:159], v[192:195], v[38:41]
	v_mfma_f32_16x16x32_bf16 v[34:37], v[164:167], v[192:195], v[34:37]
	v_mfma_f32_16x16x32_bf16 v[22:25], v[156:159], v[200:203], v[22:25]
	v_mfma_f32_16x16x32_bf16 v[18:21], v[164:167], v[200:203], v[18:21]
	v_mfma_f32_16x16x32_bf16 v[6:9], v[156:159], v[208:211], v[6:9]
	v_mfma_f32_16x16x32_bf16 v[2:5], v[164:167], v[208:211], v[2:5]
	s_setprio 0
	s_barrier
	s_add_i32 s56, s56, 2
	s_add_u32 s54, s54, 0x100
	s_addc_u32 s55, s55, 0
	s_cmp_gt_u32 s56, 13
	s_mov_b64 s[78:79], s[80:81]
	s_cbranch_scc0 .LBB0_1036

; #define PG8_STAGE(bufoff, gbase, voff) do { _Pragma("unroll") for (int _i = 0; _i < 2; ++_i) \
;         __builtin_amdgcn_global_load_lds((const unsigned*)((const char*)(gbase) + (voff)[_i]), (PG8_LAS unsigned*)(lds + (bufoff) + ldsw + _i * 8192), 16, 0, 0); } while (0)
; #define PG8_LDA(dst, b, h) do { _Pragma("unroll") for (int m = 0; m < 4; ++m) _Pragma("unroll") for (int k = 0; k < 2; ++k) dst[m][k] = *(const PG8_LAS bf16x8*)(lds + PG8_SA(b, h) + aoff + m * 2048 + k * 1024); } while (0)
; #define PG8_LDB(dst, b, h) do { _Pragma("unroll") for (int n = 0; n < 2; ++n) _Pragma("unroll") for (int k = 0; k < 2; ++k) dst[n][k] = *(const PG8_LAS bf16x8*)(lds + PG8_SB(b, h) + boff + n * 2048 + k * 1024); } while (0)
; #define PG8_WAIT_V(n) asm volatile("s_waitcnt vmcnt(" #n ")" ::: "memory")
; #define PG8_WAIT_L(n) asm volatile("s_waitcnt lgkmcnt(" #n ")" ::: "memory")
; #define PG8_BAR __builtin_amdgcn_s_barrier()
; #define PG8_SCHED __builtin_amdgcn_sched_barrier(0)
; template <class Epi, class Sched, bool ALIGN_EPI = false, bool SP2 = false>
; __device__ __forceinline__ void gemm_phase(PG8_LAS unsigned char* lds, const Gemm g, const Sched& S, const Epi& E) {
;     ...
;         const bool has_next = S.next(ui + 1, nxt);
;         const char* nA = has_next ? (const char*)g.A + (size_t)nxt.pm * tstep : cA; const char* nB = has_next ? (const char*)g.Bt + (size_t)nxt.pn * tstep : cB;
;         for (int t = 0; t < nt; t += 2) {
;             const bool last = (t == nt - 2);
;             const char* a1 = cA + (size_t)(t + 1) * kstep;
;             const char* a2 = last ? nA : cA + (size_t)(t + 2) * kstep; const char* b2 = last ? nB : cB + (size_t)(t + 2) * kstep;
;             const char* a3 = a2 + kstep; const char* b3 = b2 + kstep;
;             if (last && has_next) S.a_ready(nxt);
;             if constexpr (SP2) {
;             PG8_LDB(B0, 0, 0); PG8_LDB(B1, 0, 1); PG8_SCHED; PG8_LDA(At, 0, 0); PG8_STAGE(PG8_SA(1, 1), a1 + hstep, voffA);
;             PG8_WAIT_V(8); PG8_WAIT_L(0); PG8_BAR; PG8_MMA(0, 0, At, B0); PG8_MMA(0, 1, At, B1); PG8_BAR; PG8_SCHED;
;             PG8_LDA(At, 0, 1); PG8_STAGE(PG8_SB(0, 0), b2, voffB); PG8_STAGE(PG8_SB(0, 1), b2 + hstep, voffB); PG8_STAGE(PG8_SA(0, 0), a2, voffA);
;             PG8_WAIT_V(8); PG8_WAIT_L(0); PG8_BAR; PG8_MMA(1, 0, At, B0); PG8_MMA(1, 1, At, B1); PG8_BAR; PG8_SCHED;
.LBB0_1123:
	s_ashr_i32 s73, s72, 31
	s_lshl_b64 s[52:53], s[72:73], 19
	s_add_u32 s74, s42, s52
	s_addc_u32 s75, s43, s53
	s_and_b64 s[52:53], s[6:7], exec
	s_cselect_b32 s73, s75, s1
	s_cselect_b32 s86, s74, s0
	s_ashr_i32 s71, s70, 31
	s_lshl_b64 s[52:53], s[70:71], 19
	s_add_u32 s76, s24, s52
	s_addc_u32 s77, s25, s53
	s_and_b64 s[52:53], s[6:7], exec
	s_cselect_b32 s52, s77, s79
	s_cselect_b32 s53, s76, s78
	s_add_u32 s0, s0, 0x40080
	s_addc_u32 s1, s1, 0
	s_add_u32 s71, s78, 0x100
	s_addc_u32 s54, s79, 0
	s_mov_b32 s55, -2
	s_waitcnt vmcnt(0)
	s_add_u32 s50, s0, 0xfffc0080
	s_addc_u32 s51, s1, -1
	s_add_i32 s56, 0, 0x10000
	s_cmp_eq_u32 s55, 12
	s_cselect_b32 s81, s73, s51
	s_cselect_b32 s80, s86, s50
	s_cselect_b32 s79, s52, s54
	s_cselect_b32 s78, s53, s71
	s_add_i32 s50, 0, 0x14000
	v_add_u32_e32 v142, s56, v174
	v_add_u32_e32 v170, s50, v174
	ds_read_b128 v[130:133], v142
	ds_read_b128 v[134:137], v142 offset:1024
	ds_read_b128 v[138:141], v142 offset:2048
	ds_read_b128 v[142:145], v142 offset:3072
	ds_read_b128 v[146:149], v170
	ds_read_b128 v[150:153], v170 offset:1024
	ds_read_b128 v[154:157], v170 offset:2048
	ds_read_b128 v[178:181], v170 offset:3072
	v_lshl_add_u64 v[170:171], s[0:1], 0, v[166:167]
	s_add_i32 m0, s62, 0xc000
	ds_read_b128 v[182:185], v176
	ds_read_b128 v[192:195], v176 offset:1024
	ds_read_b128 v[196:199], v176 offset:2048
	ds_read_b128 v[200:203], v176 offset:3072
	ds_read_b128 v[204:207], v176 offset:4096
	ds_read_b128 v[208:211], v176 offset:5120
	ds_read_b128 v[212:215], v176 offset:6144
	ds_read_b128 v[216:219], v176 offset:7168
	global_load_lds_dwordx4 v[170:171], off
	v_lshl_add_u64 v[170:171], s[0:1], 0, v[168:169]
	s_add_i32 m0, s62, 0xe000
	s_nop 0
	global_load_lds_dwordx4 v[170:171], off
	s_cmp_lg_u32 s100, 0
	s_cbranch_scc1 .Lpe_skipP_mq_0
	s_waitcnt vmcnt(8)
.Lpe_skipP_mq_0:
	s_waitcnt lgkmcnt(0)
	s_barrier
	s_setprio 1
	s_waitcnt lgkmcnt(0)
	v_mfma_f32_16x16x32_bf16 v[126:129], v[130:133], v[182:185], 0
	v_mfma_f32_16x16x32_bf16 v[122:125], v[138:141], v[182:185], 0
	v_mfma_f32_16x16x32_bf16 v[114:117], v[130:133], v[196:199], 0
	v_mfma_f32_16x16x32_bf16 v[106:109], v[138:141], v[196:199], 0
	v_mfma_f32_16x16x32_bf16 v[98:101], v[130:133], v[204:207], 0
	v_mfma_f32_16x16x32_bf16 v[90:93], v[138:141], v[204:207], 0
	v_mfma_f32_16x16x32_bf16 v[82:85], v[130:133], v[212:215], 0
	v_mfma_f32_16x16x32_bf16 v[74:77], v[138:141], v[212:215], 0
	v_mfma_f32_16x16x32_bf16 v[126:129], v[134:137], v[192:195], v[126:129]
	v_mfma_f32_16x16x32_bf16 v[122:125], v[142:145], v[192:195], v[122:125]
	v_mfma_f32_16x16x32_bf16 v[114:117], v[134:137], v[200:203], v[114:117]
	v_mfma_f32_16x16x32_bf16 v[106:109], v[142:145], v[200:203], v[106:109]
	v_mfma_f32_16x16x32_bf16 v[98:101], v[134:137], v[208:211], v[98:101]
	v_mfma_f32_16x16x32_bf16 v[90:93], v[142:145], v[208:211], v[90:93]
	v_mfma_f32_16x16x32_bf16 v[82:85], v[134:137], v[216:219], v[82:85]
	v_mfma_f32_16x16x32_bf16 v[74:77], v[142:145], v[216:219], v[74:77]
	s_setprio 0
	s_setprio 1
	v_mfma_f32_16x16x32_bf16 v[118:121], v[146:149], v[182:185], 0
	v_mfma_f32_16x16x32_bf16 v[110:113], v[154:157], v[182:185], 0
	v_mfma_f32_16x16x32_bf16 v[102:105], v[146:149], v[196:199], 0
	v_mfma_f32_16x16x32_bf16 v[94:97], v[154:157], v[196:199], 0
	v_mfma_f32_16x16x32_bf16 v[86:89], v[146:149], v[204:207], 0
	v_mfma_f32_16x16x32_bf16 v[78:81], v[154:157], v[204:207], 0
	v_mfma_f32_16x16x32_bf16 v[70:73], v[146:149], v[212:215], 0
	v_mfma_f32_16x16x32_bf16 v[66:69], v[154:157], v[212:215], 0
	v_mfma_f32_16x16x32_bf16 v[118:121], v[150:153], v[192:195], v[118:121]
	v_mfma_f32_16x16x32_bf16 v[110:113], v[178:181], v[192:195], v[110:113]
	v_mfma_f32_16x16x32_bf16 v[102:105], v[150:153], v[200:203], v[102:105]
	v_mfma_f32_16x16x32_bf16 v[94:97], v[178:181], v[200:203], v[94:97]
	v_mfma_f32_16x16x32_bf16 v[86:89], v[150:153], v[208:211], v[86:89]
	v_mfma_f32_16x16x32_bf16 v[78:81], v[178:181], v[208:211], v[78:81]
	v_mfma_f32_16x16x32_bf16 v[70:73], v[150:153], v[216:219], v[70:73]
	v_mfma_f32_16x16x32_bf16 v[66:69], v[178:181], v[216:219], v[66:69]
	s_setprio 0
	s_barrier
	s_add_i32 s51, s56, s35
	v_lshl_add_u64 v[170:171], s[78:79], 0, v[0:1]
	s_mov_b32 m0, s51
	ds_read_b128 v[182:185], v176 offset:16384
	ds_read_b128 v[192:195], v176 offset:17408
	ds_read_b128 v[196:199], v176 offset:18432
	ds_read_b128 v[200:203], v176 offset:19456
	ds_read_b128 v[204:207], v176 offset:20480
	ds_read_b128 v[208:211], v176 offset:21504
	ds_read_b128 v[212:215], v176 offset:22528
	ds_read_b128 v[216:219], v176 offset:23552
	global_load_lds_dwordx4 v[170:171], off
	s_add_i32 m0, s51, 0x2000
	s_add_u32 s56, s78, 0x40000
	v_lshl_add_u64 v[188:189], s[78:79], 0, v[158:159]
	s_addc_u32 s57, s79, 0
	s_add_i32 s50, s50, s35
	global_load_lds_dwordx4 v[188:189], off
	v_lshl_add_u64 v[190:191], s[56:57], 0, v[0:1]
	s_mov_b32 m0, s50
	v_lshl_add_u64 v[220:221], s[80:81], 0, v[160:161]
	global_load_lds_dwordx4 v[190:191], off
	v_lshl_add_u64 v[190:191], s[56:57], 0, v[158:159]
	s_add_i32 m0, s50, 0x2000
	s_nop 0
	global_load_lds_dwordx4 v[190:191], off
	v_lshl_add_u64 v[190:191], s[80:81], 0, v[162:163]
	s_mov_b32 m0, s62
	s_nop 0
	global_load_lds_dwordx4 v[190:191], off
	s_mov_b32 m0, s63
	s_nop 0
	global_load_lds_dwordx4 v[220:221], off
	s_cmp_lg_u32 s100, 0
	s_cbranch_scc1 .Lpe_skipP_mq_1
	s_waitcnt vmcnt(8)
; #define PG8_STAGE(bufoff, gbase, voff) do { _Pragma("unroll") for (int _i = 0; _i < 2; ++_i) \
;         __builtin_amdgcn_global_load_lds((const unsigned*)((const char*)(gbase) + (voff)[_i]), (PG8_LAS unsigned*)(lds + (bufoff) + ldsw + _i * 8192), 16, 0, 0); } while (0)
; #define PG8_LDA(dst, b, h) do { _Pragma("unroll") for (int m = 0; m < 4; ++m) _Pragma("unroll") for (int k = 0; k < 2; ++k) dst[m][k] = *(const PG8_LAS bf16x8*)(lds + PG8_SA(b, h) + aoff + m * 2048 + k * 1024); } while (0)
; #define PG8_LDB(dst, b, h) do { _Pragma("unroll") for (int n = 0; n < 2; ++n) _Pragma("unroll") for (int k = 0; k < 2; ++k) dst[n][k] = *(const PG8_LAS bf16x8*)(lds + PG8_SB(b, h) + boff + n * 2048 + k * 1024); } while (0)
; #define PG8_MMA(ai, bj, At, Bt) do { __builtin_amdgcn_s_setprio(1); _Pragma("unroll") for (int m = 0; m < 4; ++m) _Pragma("unroll") for (int n = 0; n < 2; ++n) _Pragma("unroll") for (int k = 0; k < 2; ++k) \
;         acc[ai][bj][m][n] = __builtin_amdgcn_mfma_f32_16x16x32_bf16(Bt[n][k], At[m][k], acc[ai][bj][m][n], 0, 0, 0); __builtin_amdgcn_s_setprio(0); } while (0)
; #define PG8_WAIT_V(n) asm volatile("s_waitcnt vmcnt(" #n ")" ::: "memory")
; #define PG8_WAIT_L(n) asm volatile("s_waitcnt lgkmcnt(" #n ")" ::: "memory")
; #define PG8_BAR __builtin_amdgcn_s_barrier()
; #define PG8_SCHED __builtin_amdgcn_sched_barrier(0)
; template <class Epi, class Sched, bool ALIGN_EPI = false, bool SP2 = false>
; __device__ __forceinline__ void gemm_phase(PG8_LAS unsigned char* lds, const Gemm g, const Sched& S, const Epi& E) {
;     ...
;             PG8_WAIT_V(8); PG8_WAIT_L(0); PG8_BAR; PG8_MMA(1, 0, At, B0); PG8_MMA(1, 1, At, B1); PG8_BAR; PG8_SCHED;
;             PG8_LDB(B0, 1, 0); PG8_LDB(B1, 1, 1); PG8_SCHED; PG8_LDA(At, 1, 0); PG8_STAGE(PG8_SA(0, 1), a2 + hstep, voffA);
;             PG8_WAIT_V(8); PG8_WAIT_L(0); PG8_BAR; PG8_MMA(0, 0, At, B0); PG8_MMA(0, 1, At, B1); PG8_BAR; PG8_SCHED;
.Lpe_skipP_mq_1:
	s_mov_b32 s100, 0
	s_waitcnt lgkmcnt(0)
	s_barrier
	s_setprio 1
	s_waitcnt lgkmcnt(0)
	v_mfma_f32_16x16x32_bf16 v[62:65], v[130:133], v[182:185], 0
	v_mfma_f32_16x16x32_bf16 v[58:61], v[138:141], v[182:185], 0
	v_mfma_f32_16x16x32_bf16 v[50:53], v[130:133], v[196:199], 0
	v_mfma_f32_16x16x32_bf16 v[42:45], v[138:141], v[196:199], 0
	v_mfma_f32_16x16x32_bf16 v[34:37], v[130:133], v[204:207], 0
	v_mfma_f32_16x16x32_bf16 v[26:29], v[138:141], v[204:207], 0
	v_mfma_f32_16x16x32_bf16 v[18:21], v[130:133], v[212:215], 0
	v_mfma_f32_16x16x32_bf16 v[10:13], v[138:141], v[212:215], 0
	v_mfma_f32_16x16x32_bf16 v[62:65], v[134:137], v[192:195], v[62:65]
	v_mfma_f32_16x16x32_bf16 v[58:61], v[142:145], v[192:195], v[58:61]
	v_mfma_f32_16x16x32_bf16 v[50:53], v[134:137], v[200:203], v[50:53]
	v_mfma_f32_16x16x32_bf16 v[42:45], v[142:145], v[200:203], v[42:45]
	v_mfma_f32_16x16x32_bf16 v[34:37], v[134:137], v[208:211], v[34:37]
	v_mfma_f32_16x16x32_bf16 v[26:29], v[142:145], v[208:211], v[26:29]
	v_mfma_f32_16x16x32_bf16 v[18:21], v[134:137], v[216:219], v[18:21]
	v_mfma_f32_16x16x32_bf16 v[10:13], v[142:145], v[216:219], v[10:13]
	s_setprio 0
	s_setprio 1
	v_mfma_f32_16x16x32_bf16 v[54:57], v[146:149], v[182:185], 0
	v_mfma_f32_16x16x32_bf16 v[46:49], v[154:157], v[182:185], 0
	v_mfma_f32_16x16x32_bf16 v[38:41], v[146:149], v[196:199], 0
	v_mfma_f32_16x16x32_bf16 v[30:33], v[154:157], v[196:199], 0
	v_mfma_f32_16x16x32_bf16 v[22:25], v[146:149], v[204:207], 0
	v_mfma_f32_16x16x32_bf16 v[14:17], v[154:157], v[204:207], 0
	v_mfma_f32_16x16x32_bf16 v[6:9], v[146:149], v[212:215], 0
	v_mfma_f32_16x16x32_bf16 v[2:5], v[154:157], v[212:215], 0
	v_mfma_f32_16x16x32_bf16 v[54:57], v[150:153], v[192:195], v[54:57]
	v_mfma_f32_16x16x32_bf16 v[46:49], v[178:181], v[192:195], v[46:49]
	v_mfma_f32_16x16x32_bf16 v[38:41], v[150:153], v[200:203], v[38:41]
	v_mfma_f32_16x16x32_bf16 v[30:33], v[178:181], v[200:203], v[30:33]
	v_mfma_f32_16x16x32_bf16 v[22:25], v[150:153], v[208:211], v[22:25]
	v_mfma_f32_16x16x32_bf16 v[14:17], v[178:181], v[208:211], v[14:17]
	v_mfma_f32_16x16x32_bf16 v[6:9], v[150:153], v[216:219], v[6:9]
	v_mfma_f32_16x16x32_bf16 v[2:5], v[178:181], v[216:219], v[2:5]
	s_setprio 0
	s_barrier
	s_add_i32 s50, 0, 0x18000
	s_add_i32 s51, 0, 0x1c000
	v_add_u32_e32 v142, s50, v174
	v_add_u32_e32 v172, s51, v174
	ds_read_b128 v[130:133], v142
	ds_read_b128 v[134:137], v142 offset:1024
	ds_read_b128 v[138:141], v142 offset:2048
	ds_read_b128 v[142:145], v142 offset:3072
	ds_read_b128 v[146:149], v172
	ds_read_b128 v[150:153], v172 offset:1024
	ds_read_b128 v[154:157], v172 offset:2048
	ds_read_b128 v[178:181], v172 offset:3072
	s_add_u32 s56, s80, 0x40000
	s_addc_u32 s57, s81, 0
	s_mov_b32 m0, s64
	v_lshl_add_u64 v[222:223], s[56:57], 0, v[162:163]
	ds_read_b128 v[182:185], v176 offset:32768
	ds_read_b128 v[192:195], v176 offset:33792
	ds_read_b128 v[196:199], v176 offset:34816
	ds_read_b128 v[200:203], v176 offset:35840
	ds_read_b128 v[204:207], v176 offset:36864
	ds_read_b128 v[208:211], v176 offset:37888
	ds_read_b128 v[212:215], v176 offset:38912
	ds_read_b128 v[216:219], v176 offset:39936
	global_load_lds_dwordx4 v[222:223], off
	v_lshl_add_u64 v[222:223], s[56:57], 0, v[160:161]
	s_mov_b32 m0, s82
	s_nop 0
	global_load_lds_dwordx4 v[222:223], off
	s_waitcnt vmcnt(8)
	s_waitcnt lgkmcnt(0)
	s_barrier
	s_setprio 1
	s_waitcnt lgkmcnt(0)
	v_mfma_f32_16x16x32_bf16 v[126:129], v[130:133], v[182:185], v[126:129]
	v_mfma_f32_16x16x32_bf16 v[122:125], v[138:141], v[182:185], v[122:125]
	v_mfma_f32_16x16x32_bf16 v[114:117], v[130:133], v[196:199], v[114:117]
	v_mfma_f32_16x16x32_bf16 v[106:109], v[138:141], v[196:199], v[106:109]
	v_mfma_f32_16x16x32_bf16 v[98:101], v[130:133], v[204:207], v[98:101]
	v_mfma_f32_16x16x32_bf16 v[90:93], v[138:141], v[204:207], v[90:93]
	v_mfma_f32_16x16x32_bf16 v[82:85], v[130:133], v[212:215], v[82:85]
	v_mfma_f32_16x16x32_bf16 v[74:77], v[138:141], v[212:215], v[74:77]
	v_mfma_f32_16x16x32_bf16 v[126:129], v[134:137], v[192:195], v[126:129]
	v_mfma_f32_16x16x32_bf16 v[122:125], v[142:145], v[192:195], v[122:125]
	v_mfma_f32_16x16x32_bf16 v[114:117], v[134:137], v[200:203], v[114:117]
	v_mfma_f32_16x16x32_bf16 v[106:109], v[142:145], v[200:203], v[106:109]
	v_mfma_f32_16x16x32_bf16 v[98:101], v[134:137], v[208:211], v[98:101]
	v_mfma_f32_16x16x32_bf16 v[90:93], v[142:145], v[208:211], v[90:93]
	v_mfma_f32_16x16x32_bf16 v[82:85], v[134:137], v[216:219], v[82:85]
	v_mfma_f32_16x16x32_bf16 v[74:77], v[142:145], v[216:219], v[74:77]
	s_setprio 0
	s_setprio 1
	v_mfma_f32_16x16x32_bf16 v[118:121], v[146:149], v[182:185], v[118:121]
	v_mfma_f32_16x16x32_bf16 v[110:113], v[154:157], v[182:185], v[110:113]
	v_mfma_f32_16x16x32_bf16 v[102:105], v[146:149], v[196:199], v[102:105]
	v_mfma_f32_16x16x32_bf16 v[94:97], v[154:157], v[196:199], v[94:97]
	v_mfma_f32_16x16x32_bf16 v[86:89], v[146:149], v[204:207], v[86:89]
	v_mfma_f32_16x16x32_bf16 v[78:81], v[154:157], v[204:207], v[78:81]
	v_mfma_f32_16x16x32_bf16 v[70:73], v[146:149], v[212:215], v[70:73]
	v_mfma_f32_16x16x32_bf16 v[66:69], v[154:157], v[212:215], v[66:69]
	v_mfma_f32_16x16x32_bf16 v[118:121], v[150:153], v[192:195], v[118:121]
	v_mfma_f32_16x16x32_bf16 v[110:113], v[178:181], v[192:195], v[110:113]
	v_mfma_f32_16x16x32_bf16 v[102:105], v[150:153], v[200:203], v[102:105]
	v_mfma_f32_16x16x32_bf16 v[94:97], v[178:181], v[200:203], v[94:97]
	v_mfma_f32_16x16x32_bf16 v[86:89], v[150:153], v[208:211], v[86:89]
	v_mfma_f32_16x16x32_bf16 v[78:81], v[178:181], v[208:211], v[78:81]
	v_mfma_f32_16x16x32_bf16 v[70:73], v[150:153], v[216:219], v[70:73]
	v_mfma_f32_16x16x32_bf16 v[66:69], v[178:181], v[216:219], v[66:69]
	s_setprio 0
	s_barrier
; #define PG8_STAGE(bufoff, gbase, voff) do { _Pragma("unroll") for (int _i = 0; _i < 2; ++_i) \
;         __builtin_amdgcn_global_load_lds((const unsigned*)((const char*)(gbase) + (voff)[_i]), (PG8_LAS unsigned*)(lds + (bufoff) + ldsw + _i * 8192), 16, 0, 0); } while (0)
; #define PG8_LDA(dst, b, h) do { _Pragma("unroll") for (int m = 0; m < 4; ++m) _Pragma("unroll") for (int k = 0; k < 2; ++k) dst[m][k] = *(const PG8_LAS bf16x8*)(lds + PG8_SA(b, h) + aoff + m * 2048 + k * 1024); } while (0)
; #define PG8_MMA(ai, bj, At, Bt) do { __builtin_amdgcn_s_setprio(1); _Pragma("unroll") for (int m = 0; m < 4; ++m) _Pragma("unroll") for (int n = 0; n < 2; ++n) _Pragma("unroll") for (int k = 0; k < 2; ++k) \
;         acc[ai][bj][m][n] = __builtin_amdgcn_mfma_f32_16x16x32_bf16(Bt[n][k], At[m][k], acc[ai][bj][m][n], 0, 0, 0); __builtin_amdgcn_s_setprio(0); } while (0)
; #define PG8_WAIT_V(n) asm volatile("s_waitcnt vmcnt(" #n ")" ::: "memory")
; #define PG8_WAIT_L(n) asm volatile("s_waitcnt lgkmcnt(" #n ")" ::: "memory")
; #define PG8_BAR __builtin_amdgcn_s_barrier()
; #define PG8_SCHED __builtin_amdgcn_sched_barrier(0)
; template <class Epi, class Sched, bool ALIGN_EPI = false, bool SP2 = false>
; __device__ __forceinline__ void gemm_phase(PG8_LAS unsigned char* lds, const Gemm g, const Sched& S, const Epi& E) {
;     ...
;             PG8_LDA(At, 1, 1); PG8_STAGE(PG8_SB(1, 0), b3, voffB); PG8_STAGE(PG8_SB(1, 1), b3 + hstep, voffB); PG8_STAGE(PG8_SA(1, 0), a3, voffA);
;             PG8_WAIT_V(8); PG8_WAIT_L(0); PG8_BAR; PG8_MMA(1, 0, At, B0); PG8_MMA(1, 1, At, B1); PG8_BAR; PG8_SCHED;
	s_add_i32 s50, s50, s35
	v_lshl_add_u64 v[170:171], v[170:171], 0, s[60:61]
	s_mov_b32 m0, s50
	ds_read_b128 v[182:185], v176 offset:49152
	ds_read_b128 v[192:195], v176 offset:50176
	ds_read_b128 v[196:199], v176 offset:51200
	ds_read_b128 v[200:203], v176 offset:52224
	ds_read_b128 v[204:207], v176 offset:53248
	ds_read_b128 v[208:211], v176 offset:54272
	ds_read_b128 v[212:215], v176 offset:55296
	ds_read_b128 v[216:219], v176 offset:56320
	global_load_lds_dwordx4 v[170:171], off
	s_add_i32 m0, s50, 0x2000
	s_add_u32 s56, s78, 0x40080
	v_lshl_add_u64 v[170:171], v[188:189], 0, s[60:61]
	s_addc_u32 s57, s79, 0
	s_add_i32 s50, s51, s35
	global_load_lds_dwordx4 v[170:171], off
	v_lshl_add_u64 v[170:171], s[56:57], 0, v[0:1]
	s_mov_b32 m0, s50
	s_nop 0
	global_load_lds_dwordx4 v[170:171], off
	v_lshl_add_u64 v[170:171], s[56:57], 0, v[158:159]
	s_add_i32 m0, s50, 0x2000
	s_nop 0
	global_load_lds_dwordx4 v[170:171], off
	v_lshl_add_u64 v[170:171], v[190:191], 0, s[60:61]
	s_mov_b32 m0, s83
	s_nop 0
	global_load_lds_dwordx4 v[170:171], off
	v_lshl_add_u64 v[170:171], v[220:221], 0, s[60:61]
	s_mov_b32 m0, s84
	s_nop 0
	global_load_lds_dwordx4 v[170:171], off
	s_waitcnt vmcnt(8)
	s_waitcnt lgkmcnt(0)
	s_barrier
	s_setprio 1
	s_waitcnt lgkmcnt(0)
	v_mfma_f32_16x16x32_bf16 v[62:65], v[130:133], v[182:185], v[62:65]
	v_mfma_f32_16x16x32_bf16 v[58:61], v[138:141], v[182:185], v[58:61]
	v_mfma_f32_16x16x32_bf16 v[50:53], v[130:133], v[196:199], v[50:53]
	v_mfma_f32_16x16x32_bf16 v[42:45], v[138:141], v[196:199], v[42:45]
	v_mfma_f32_16x16x32_bf16 v[34:37], v[130:133], v[204:207], v[34:37]
	v_mfma_f32_16x16x32_bf16 v[26:29], v[138:141], v[204:207], v[26:29]
	v_mfma_f32_16x16x32_bf16 v[18:21], v[130:133], v[212:215], v[18:21]
	v_mfma_f32_16x16x32_bf16 v[10:13], v[138:141], v[212:215], v[10:13]
	v_mfma_f32_16x16x32_bf16 v[62:65], v[134:137], v[192:195], v[62:65]
	v_mfma_f32_16x16x32_bf16 v[58:61], v[142:145], v[192:195], v[58:61]
	v_mfma_f32_16x16x32_bf16 v[50:53], v[134:137], v[200:203], v[50:53]
	v_mfma_f32_16x16x32_bf16 v[42:45], v[142:145], v[200:203], v[42:45]
	v_mfma_f32_16x16x32_bf16 v[34:37], v[134:137], v[208:211], v[34:37]
	v_mfma_f32_16x16x32_bf16 v[26:29], v[142:145], v[208:211], v[26:29]
	v_mfma_f32_16x16x32_bf16 v[18:21], v[134:137], v[216:219], v[18:21]
	v_mfma_f32_16x16x32_bf16 v[10:13], v[142:145], v[216:219], v[10:13]
	s_setprio 0
	s_setprio 1
	v_mfma_f32_16x16x32_bf16 v[54:57], v[146:149], v[182:185], v[54:57]
	v_mfma_f32_16x16x32_bf16 v[46:49], v[154:157], v[182:185], v[46:49]
	v_mfma_f32_16x16x32_bf16 v[38:41], v[146:149], v[196:199], v[38:41]
	v_mfma_f32_16x16x32_bf16 v[30:33], v[154:157], v[196:199], v[30:33]
	v_mfma_f32_16x16x32_bf16 v[22:25], v[146:149], v[204:207], v[22:25]
	v_mfma_f32_16x16x32_bf16 v[14:17], v[154:157], v[204:207], v[14:17]
	v_mfma_f32_16x16x32_bf16 v[6:9], v[146:149], v[212:215], v[6:9]
	v_mfma_f32_16x16x32_bf16 v[2:5], v[154:157], v[212:215], v[2:5]
	v_mfma_f32_16x16x32_bf16 v[54:57], v[150:153], v[192:195], v[54:57]
	v_mfma_f32_16x16x32_bf16 v[46:49], v[178:181], v[192:195], v[46:49]
	v_mfma_f32_16x16x32_bf16 v[38:41], v[150:153], v[200:203], v[38:41]
	v_mfma_f32_16x16x32_bf16 v[30:33], v[178:181], v[200:203], v[30:33]
	v_mfma_f32_16x16x32_bf16 v[22:25], v[150:153], v[208:211], v[22:25]
	v_mfma_f32_16x16x32_bf16 v[14:17], v[178:181], v[208:211], v[14:17]
	v_mfma_f32_16x16x32_bf16 v[6:9], v[150:153], v[216:219], v[6:9]
	v_mfma_f32_16x16x32_bf16 v[2:5], v[178:181], v[216:219], v[2:5]
	s_setprio 0
	s_barrier
	s_add_i32 s55, s55, 2
	s_add_u32 s0, s0, 0x100
	s_addc_u32 s1, s1, 0
	s_add_u32 s71, s71, 0x100
	s_addc_u32 s54, s54, 0
	s_cmp_gt_u32 s55, 13
	s_cbranch_scc0 .LBB0_1124

; #define PG8_STAGE(bufoff, gbase, voff) do { _Pragma("unroll") for (int _i = 0; _i < 2; ++_i) \
;         __builtin_amdgcn_global_load_lds((const unsigned*)((const char*)(gbase) + (voff)[_i]), (PG8_LAS unsigned*)(lds + (bufoff) + ldsw + _i * 8192), 16, 0, 0); } while (0)
; #define PG8_LDA(dst, b, h) do { _Pragma("unroll") for (int m = 0; m < 4; ++m) _Pragma("unroll") for (int k = 0; k < 2; ++k) dst[m][k] = *(const PG8_LAS bf16x8*)(lds + PG8_SA(b, h) + aoff + m * 2048 + k * 1024); } while (0)
; #define PG8_LDB(dst, b, h) do { _Pragma("unroll") for (int n = 0; n < 2; ++n) _Pragma("unroll") for (int k = 0; k < 2; ++k) dst[n][k] = *(const PG8_LAS bf16x8*)(lds + PG8_SB(b, h) + boff + n * 2048 + k * 1024); } while (0)
; template <class Epi, class Sched, bool ALIGN_EPI = false, bool SP2 = false>
; __device__ __forceinline__ void gemm_phase(PG8_LAS unsigned char* lds, const Gemm g, const Sched& S, const Epi& E) {
;     ...
;         const bool has_next = S.next(ui + 1, nxt);
;         const char* nA = has_next ? (const char*)g.A + (size_t)nxt.pm * tstep : cA; const char* nB = has_next ? (const char*)g.Bt + (size_t)nxt.pn * tstep : cB;
;         for (int t = 0; t < nt; t += 2) {
;             const bool last = (t == nt - 2);
;             const char* a1 = cA + (size_t)(t + 1) * kstep;
;             const char* a2 = last ? nA : cA + (size_t)(t + 2) * kstep; const char* b2 = last ? nB : cB + (size_t)(t + 2) * kstep;
;             const char* a3 = a2 + kstep; const char* b3 = b2 + kstep;
;             if (last && has_next) S.a_ready(nxt);
;             if constexpr (SP2) {
;             PG8_LDB(B0, 0, 0); PG8_LDB(B1, 0, 1); PG8_SCHED; PG8_LDA(At, 0, 0); PG8_STAGE(PG8_SA(1, 1), a1 + hstep, voffA);
;             PG8_WAIT_V(8); PG8_WAIT_L(0); PG8_BAR; PG8_MMA(0, 0, At, B0); PG8_MMA(0, 1, At, B1); PG8_BAR; PG8_SCHED;
;             PG8_LDA(At, 0, 1); PG8_STAGE(PG8_SB(0, 0), b2, voffB); PG8_STAGE(PG8_SB(0, 1), b2 + hstep, voffB); PG8_STAGE(PG8_SA(0, 0), a2, voffA);
;             PG8_WAIT_V(8); PG8_WAIT_L(0); PG8_BAR; PG8_MMA(1, 0, At, B0); PG8_MMA(1, 1, At, B1); PG8_BAR; PG8_SCHED;
;     ...
;         for (int a = 0; a < 2; ++a)
; #pragma unroll
;             for (int b = 0; b < 2; ++b)
; #pragma unroll
;                 for (int m = 0; m < 4; ++m)
; #pragma unroll
;                     for (int n = 0; n < 2; ++n) acc[a][b][m][n] = (f32x4){0.f, 0.f, 0.f, 0.f};
.LBB0_1262:
	s_ashr_i32 s71, s70, 31
	s_lshl_b64 s[52:53], s[70:71], 19
	s_add_u32 s72, s2, s52
	s_addc_u32 s73, s3, s53
	s_and_b64 s[52:53], s[8:9], exec
	s_cselect_b32 s52, s73, s77
	s_cselect_b32 s53, s72, s76
	s_ashr_i32 s11, s10, 31
	s_lshl_b64 s[54:55], s[10:11], 19
	s_add_u32 s74, s24, s54
	s_addc_u32 s75, s25, s55
	s_and_b64 s[54:55], s[8:9], exec
	s_cselect_b32 s11, s75, s79
	s_cselect_b32 s64, s74, s78
	s_add_u32 s54, s78, 0x100
	s_addc_u32 s55, s79, 0
	s_mov_b32 s56, -2
	s_waitcnt lgkmcnt(0)
	s_waitcnt vmcnt(0)
	s_add_u32 s78, s76, 0x100
	s_addc_u32 s79, s77, 0
	s_add_i32 s50, 0, 0x10000
	s_cmp_eq_u32 s56, 12
	s_cselect_b32 s83, s52, s79
	s_cselect_b32 s82, s53, s78
	s_cselect_b32 s81, s11, s55
	s_cselect_b32 s80, s64, s54
	s_add_i32 s51, 0, 0x14000
	v_add_u32_e32 v148, s50, v173
	v_add_u32_e32 v164, s51, v173
	ds_read_b128 v[136:139], v148
	ds_read_b128 v[140:143], v148 offset:1024
	ds_read_b128 v[144:147], v148 offset:2048
	ds_read_b128 v[148:151], v148 offset:3072
	ds_read_b128 v[152:155], v164
	ds_read_b128 v[156:159], v164 offset:1024
	ds_read_b128 v[160:163], v164 offset:2048
	ds_read_b128 v[164:167], v164 offset:3072
	v_lshl_add_u64 v[184:185], s[76:77], 0, v[132:133]
	s_add_i32 m0, s62, 0xc000
	ds_read_b128 v[168:171], v175
	ds_read_b128 v[176:179], v175 offset:1024
	ds_read_b128 v[180:183], v175 offset:2048
	ds_read_b128 v[192:195], v175 offset:3072
	ds_read_b128 v[196:199], v175 offset:4096
	ds_read_b128 v[200:203], v175 offset:5120
	ds_read_b128 v[204:207], v175 offset:6144
	ds_read_b128 v[208:211], v175 offset:7168
	global_load_lds_dwordx4 v[184:185], off
	v_lshl_add_u64 v[184:185], s[76:77], 0, v[134:135]
	s_add_i32 m0, s62, 0xe000
	s_nop 0
	global_load_lds_dwordx4 v[184:185], off
	s_cmp_lg_u32 s100, 0
	s_cbranch_scc1 .Lpe_skipP_mo_0
	s_waitcnt vmcnt(8)
.Lpe_skipP_mo_0:
	s_waitcnt lgkmcnt(0)
	s_barrier
	s_setprio 1
	s_waitcnt lgkmcnt(0)
	v_mfma_f32_16x16x32_bf16 v[126:129], v[136:139], v[168:171], 0
	v_mfma_f32_16x16x32_bf16 v[122:125], v[144:147], v[168:171], 0
	v_mfma_f32_16x16x32_bf16 v[110:113], v[136:139], v[180:183], 0
	v_mfma_f32_16x16x32_bf16 v[106:109], v[144:147], v[180:183], 0
	v_mfma_f32_16x16x32_bf16 v[94:97], v[136:139], v[196:199], 0
	v_mfma_f32_16x16x32_bf16 v[90:93], v[144:147], v[196:199], 0
	v_mfma_f32_16x16x32_bf16 v[78:81], v[136:139], v[204:207], 0
	v_mfma_f32_16x16x32_bf16 v[74:77], v[144:147], v[204:207], 0
	v_mfma_f32_16x16x32_bf16 v[126:129], v[140:143], v[176:179], v[126:129]
	v_mfma_f32_16x16x32_bf16 v[122:125], v[148:151], v[176:179], v[122:125]
	v_mfma_f32_16x16x32_bf16 v[110:113], v[140:143], v[192:195], v[110:113]
	v_mfma_f32_16x16x32_bf16 v[106:109], v[148:151], v[192:195], v[106:109]
	v_mfma_f32_16x16x32_bf16 v[94:97], v[140:143], v[200:203], v[94:97]
	v_mfma_f32_16x16x32_bf16 v[90:93], v[148:151], v[200:203], v[90:93]
	v_mfma_f32_16x16x32_bf16 v[78:81], v[140:143], v[208:211], v[78:81]
	v_mfma_f32_16x16x32_bf16 v[74:77], v[148:151], v[208:211], v[74:77]
	s_setprio 0
	s_setprio 1
	v_mfma_f32_16x16x32_bf16 v[118:121], v[152:155], v[168:171], 0
	v_mfma_f32_16x16x32_bf16 v[114:117], v[160:163], v[168:171], 0
	v_mfma_f32_16x16x32_bf16 v[102:105], v[152:155], v[180:183], 0
	v_mfma_f32_16x16x32_bf16 v[98:101], v[160:163], v[180:183], 0
	v_mfma_f32_16x16x32_bf16 v[86:89], v[152:155], v[196:199], 0
	v_mfma_f32_16x16x32_bf16 v[82:85], v[160:163], v[196:199], 0
	v_mfma_f32_16x16x32_bf16 v[70:73], v[152:155], v[204:207], 0
	v_mfma_f32_16x16x32_bf16 v[66:69], v[160:163], v[204:207], 0
	v_mfma_f32_16x16x32_bf16 v[118:121], v[156:159], v[176:179], v[118:121]
	v_mfma_f32_16x16x32_bf16 v[114:117], v[164:167], v[176:179], v[114:117]
	v_mfma_f32_16x16x32_bf16 v[102:105], v[156:159], v[192:195], v[102:105]
	v_mfma_f32_16x16x32_bf16 v[98:101], v[164:167], v[192:195], v[98:101]
	v_mfma_f32_16x16x32_bf16 v[86:89], v[156:159], v[200:203], v[86:89]
	v_mfma_f32_16x16x32_bf16 v[82:85], v[164:167], v[200:203], v[82:85]
	v_mfma_f32_16x16x32_bf16 v[70:73], v[156:159], v[208:211], v[70:73]
	v_mfma_f32_16x16x32_bf16 v[66:69], v[164:167], v[208:211], v[66:69]
	s_setprio 0
	s_barrier
	s_add_i32 s50, s50, s35
	v_lshl_add_u64 v[184:185], s[80:81], 0, v[0:1]
	s_mov_b32 m0, s50
	ds_read_b128 v[168:171], v175 offset:16384
	ds_read_b128 v[176:179], v175 offset:17408
	ds_read_b128 v[180:183], v175 offset:18432
	ds_read_b128 v[192:195], v175 offset:19456
	ds_read_b128 v[196:199], v175 offset:20480
	ds_read_b128 v[200:203], v175 offset:21504
	ds_read_b128 v[204:207], v175 offset:22528
	ds_read_b128 v[208:211], v175 offset:23552
	global_load_lds_dwordx4 v[184:185], off
	s_add_i32 m0, s50, 0x2000
	s_add_u32 s76, s80, 0x40000
	v_lshl_add_u64 v[188:189], s[80:81], 0, v[130:131]
	s_addc_u32 s77, s81, 0
	s_add_i32 s50, s51, s35
	global_load_lds_dwordx4 v[188:189], off
	v_lshl_add_u64 v[190:191], s[76:77], 0, v[0:1]
	s_mov_b32 m0, s50
	v_lshl_add_u64 v[212:213], s[82:83], 0, v[130:131]
	global_load_lds_dwordx4 v[190:191], off
	v_lshl_add_u64 v[190:191], s[76:77], 0, v[130:131]
	s_add_i32 m0, s50, 0x2000
	s_nop 0
	global_load_lds_dwordx4 v[190:191], off
	v_lshl_add_u64 v[190:191], s[82:83], 0, v[0:1]
	s_mov_b32 m0, s62
	s_nop 0
	global_load_lds_dwordx4 v[190:191], off
	s_mov_b32 m0, s63
	s_nop 0
	global_load_lds_dwordx4 v[212:213], off
	s_cmp_lg_u32 s100, 0
	s_cbranch_scc1 .Lpe_skipP_mo_1
	s_waitcnt vmcnt(8)
; #define PG8_STAGE(bufoff, gbase, voff) do { _Pragma("unroll") for (int _i = 0; _i < 2; ++_i) \
;         __builtin_amdgcn_global_load_lds((const unsigned*)((const char*)(gbase) + (voff)[_i]), (PG8_LAS unsigned*)(lds + (bufoff) + ldsw + _i * 8192), 16, 0, 0); } while (0)
; #define PG8_LDA(dst, b, h) do { _Pragma("unroll") for (int m = 0; m < 4; ++m) _Pragma("unroll") for (int k = 0; k < 2; ++k) dst[m][k] = *(const PG8_LAS bf16x8*)(lds + PG8_SA(b, h) + aoff + m * 2048 + k * 1024); } while (0)
; #define PG8_LDB(dst, b, h) do { _Pragma("unroll") for (int n = 0; n < 2; ++n) _Pragma("unroll") for (int k = 0; k < 2; ++k) dst[n][k] = *(const PG8_LAS bf16x8*)(lds + PG8_SB(b, h) + boff + n * 2048 + k * 1024); } while (0)
; #define PG8_MMA(ai, bj, At, Bt) do { __builtin_amdgcn_s_setprio(1); _Pragma("unroll") for (int m = 0; m < 4; ++m) _Pragma("unroll") for (int n = 0; n < 2; ++n) _Pragma("unroll") for (int k = 0; k < 2; ++k) \
;         acc[ai][bj][m][n] = __builtin_amdgcn_mfma_f32_16x16x32_bf16(Bt[n][k], At[m][k], acc[ai][bj][m][n], 0, 0, 0); __builtin_amdgcn_s_setprio(0); } while (0)
; #define PG8_WAIT_V(n) asm volatile("s_waitcnt vmcnt(" #n ")" ::: "memory")
; #define PG8_WAIT_L(n) asm volatile("s_waitcnt lgkmcnt(" #n ")" ::: "memory")
; #define PG8_BAR __builtin_amdgcn_s_barrier()
; #define PG8_SCHED __builtin_amdgcn_sched_barrier(0)
; template <class Epi, class Sched, bool ALIGN_EPI = false, bool SP2 = false>
; __device__ __forceinline__ void gemm_phase(PG8_LAS unsigned char* lds, const Gemm g, const Sched& S, const Epi& E) {
;     ...
;             PG8_WAIT_V(8); PG8_WAIT_L(0); PG8_BAR; PG8_MMA(1, 0, At, B0); PG8_MMA(1, 1, At, B1); PG8_BAR; PG8_SCHED;
;             PG8_LDB(B0, 1, 0); PG8_LDB(B1, 1, 1); PG8_SCHED; PG8_LDA(At, 1, 0); PG8_STAGE(PG8_SA(0, 1), a2 + hstep, voffA);
;             PG8_WAIT_V(8); PG8_WAIT_L(0); PG8_BAR; PG8_MMA(0, 0, At, B0); PG8_MMA(0, 1, At, B1); PG8_BAR; PG8_SCHED;
.Lpe_skipP_mo_1:
	s_mov_b32 s100, 0
	s_waitcnt lgkmcnt(0)
	s_barrier
	s_setprio 1
	s_waitcnt lgkmcnt(0)
	v_mfma_f32_16x16x32_bf16 v[62:65], v[136:139], v[168:171], 0
	v_mfma_f32_16x16x32_bf16 v[58:61], v[144:147], v[168:171], 0
	v_mfma_f32_16x16x32_bf16 v[46:49], v[136:139], v[180:183], 0
	v_mfma_f32_16x16x32_bf16 v[42:45], v[144:147], v[180:183], 0
	v_mfma_f32_16x16x32_bf16 v[30:33], v[136:139], v[196:199], 0
	v_mfma_f32_16x16x32_bf16 v[26:29], v[144:147], v[196:199], 0
	v_mfma_f32_16x16x32_bf16 v[14:17], v[136:139], v[204:207], 0
	v_mfma_f32_16x16x32_bf16 v[10:13], v[144:147], v[204:207], 0
	v_mfma_f32_16x16x32_bf16 v[62:65], v[140:143], v[176:179], v[62:65]
	v_mfma_f32_16x16x32_bf16 v[58:61], v[148:151], v[176:179], v[58:61]
	v_mfma_f32_16x16x32_bf16 v[46:49], v[140:143], v[192:195], v[46:49]
	v_mfma_f32_16x16x32_bf16 v[42:45], v[148:151], v[192:195], v[42:45]
	v_mfma_f32_16x16x32_bf16 v[30:33], v[140:143], v[200:203], v[30:33]
	v_mfma_f32_16x16x32_bf16 v[26:29], v[148:151], v[200:203], v[26:29]
	v_mfma_f32_16x16x32_bf16 v[14:17], v[140:143], v[208:211], v[14:17]
	v_mfma_f32_16x16x32_bf16 v[10:13], v[148:151], v[208:211], v[10:13]
	s_setprio 0
	s_setprio 1
	v_mfma_f32_16x16x32_bf16 v[54:57], v[152:155], v[168:171], 0
	v_mfma_f32_16x16x32_bf16 v[50:53], v[160:163], v[168:171], 0
	v_mfma_f32_16x16x32_bf16 v[38:41], v[152:155], v[180:183], 0
	v_mfma_f32_16x16x32_bf16 v[34:37], v[160:163], v[180:183], 0
	v_mfma_f32_16x16x32_bf16 v[22:25], v[152:155], v[196:199], 0
	v_mfma_f32_16x16x32_bf16 v[18:21], v[160:163], v[196:199], 0
	v_mfma_f32_16x16x32_bf16 v[6:9], v[152:155], v[204:207], 0
	v_mfma_f32_16x16x32_bf16 v[2:5], v[160:163], v[204:207], 0
	v_mfma_f32_16x16x32_bf16 v[54:57], v[156:159], v[176:179], v[54:57]
	v_mfma_f32_16x16x32_bf16 v[50:53], v[164:167], v[176:179], v[50:53]
	v_mfma_f32_16x16x32_bf16 v[38:41], v[156:159], v[192:195], v[38:41]
	v_mfma_f32_16x16x32_bf16 v[34:37], v[164:167], v[192:195], v[34:37]
	v_mfma_f32_16x16x32_bf16 v[22:25], v[156:159], v[200:203], v[22:25]
	v_mfma_f32_16x16x32_bf16 v[18:21], v[164:167], v[200:203], v[18:21]
	v_mfma_f32_16x16x32_bf16 v[6:9], v[156:159], v[208:211], v[6:9]
	v_mfma_f32_16x16x32_bf16 v[2:5], v[164:167], v[208:211], v[2:5]
	s_setprio 0
	s_barrier
	s_add_i32 s50, 0, 0x18000
	s_add_i32 s51, 0, 0x1c000
	v_add_u32_e32 v148, s50, v173
	v_add_u32_e32 v164, s51, v173
	ds_read_b128 v[136:139], v148
	ds_read_b128 v[140:143], v148 offset:1024
	ds_read_b128 v[144:147], v148 offset:2048
	ds_read_b128 v[148:151], v148 offset:3072
	ds_read_b128 v[152:155], v164
	ds_read_b128 v[156:159], v164 offset:1024
	ds_read_b128 v[160:163], v164 offset:2048
	ds_read_b128 v[164:167], v164 offset:3072
	s_add_u32 s76, s82, 0x40000
	s_addc_u32 s77, s83, 0
	s_mov_b32 m0, s84
	v_lshl_add_u64 v[214:215], s[76:77], 0, v[0:1]
	ds_read_b128 v[168:171], v175 offset:32768
	ds_read_b128 v[176:179], v175 offset:33792
	ds_read_b128 v[180:183], v175 offset:34816
	ds_read_b128 v[192:195], v175 offset:35840
	ds_read_b128 v[196:199], v175 offset:36864
	ds_read_b128 v[200:203], v175 offset:37888
	ds_read_b128 v[204:207], v175 offset:38912
	ds_read_b128 v[208:211], v175 offset:39936
	global_load_lds_dwordx4 v[214:215], off
	v_lshl_add_u64 v[214:215], s[76:77], 0, v[130:131]
	s_mov_b32 m0, s85
	s_nop 0
	global_load_lds_dwordx4 v[214:215], off
	s_waitcnt vmcnt(8)
	s_waitcnt lgkmcnt(0)
	s_barrier
	s_setprio 1
	s_waitcnt lgkmcnt(0)
	v_mfma_f32_16x16x32_bf16 v[126:129], v[136:139], v[168:171], v[126:129]
	v_mfma_f32_16x16x32_bf16 v[122:125], v[144:147], v[168:171], v[122:125]
	v_mfma_f32_16x16x32_bf16 v[110:113], v[136:139], v[180:183], v[110:113]
	v_mfma_f32_16x16x32_bf16 v[106:109], v[144:147], v[180:183], v[106:109]
	v_mfma_f32_16x16x32_bf16 v[94:97], v[136:139], v[196:199], v[94:97]
	v_mfma_f32_16x16x32_bf16 v[90:93], v[144:147], v[196:199], v[90:93]
	v_mfma_f32_16x16x32_bf16 v[78:81], v[136:139], v[204:207], v[78:81]
	v_mfma_f32_16x16x32_bf16 v[74:77], v[144:147], v[204:207], v[74:77]
	v_mfma_f32_16x16x32_bf16 v[126:129], v[140:143], v[176:179], v[126:129]
	v_mfma_f32_16x16x32_bf16 v[122:125], v[148:151], v[176:179], v[122:125]
	v_mfma_f32_16x16x32_bf16 v[110:113], v[140:143], v[192:195], v[110:113]
	v_mfma_f32_16x16x32_bf16 v[106:109], v[148:151], v[192:195], v[106:109]
	v_mfma_f32_16x16x32_bf16 v[94:97], v[140:143], v[200:203], v[94:97]
	v_mfma_f32_16x16x32_bf16 v[90:93], v[148:151], v[200:203], v[90:93]
	v_mfma_f32_16x16x32_bf16 v[78:81], v[140:143], v[208:211], v[78:81]
	v_mfma_f32_16x16x32_bf16 v[74:77], v[148:151], v[208:211], v[74:77]
	s_setprio 0
	s_setprio 1
	v_mfma_f32_16x16x32_bf16 v[118:121], v[152:155], v[168:171], v[118:121]
	v_mfma_f32_16x16x32_bf16 v[114:117], v[160:163], v[168:171], v[114:117]
	v_mfma_f32_16x16x32_bf16 v[102:105], v[152:155], v[180:183], v[102:105]
	v_mfma_f32_16x16x32_bf16 v[98:101], v[160:163], v[180:183], v[98:101]
	v_mfma_f32_16x16x32_bf16 v[86:89], v[152:155], v[196:199], v[86:89]
	v_mfma_f32_16x16x32_bf16 v[82:85], v[160:163], v[196:199], v[82:85]
	v_mfma_f32_16x16x32_bf16 v[70:73], v[152:155], v[204:207], v[70:73]
	v_mfma_f32_16x16x32_bf16 v[66:69], v[160:163], v[204:207], v[66:69]
	v_mfma_f32_16x16x32_bf16 v[118:121], v[156:159], v[176:179], v[118:121]
	v_mfma_f32_16x16x32_bf16 v[114:117], v[164:167], v[176:179], v[114:117]
	v_mfma_f32_16x16x32_bf16 v[102:105], v[156:159], v[192:195], v[102:105]
	v_mfma_f32_16x16x32_bf16 v[98:101], v[164:167], v[192:195], v[98:101]
	v_mfma_f32_16x16x32_bf16 v[86:89], v[156:159], v[200:203], v[86:89]
	v_mfma_f32_16x16x32_bf16 v[82:85], v[164:167], v[200:203], v[82:85]
	v_mfma_f32_16x16x32_bf16 v[70:73], v[156:159], v[208:211], v[70:73]
	v_mfma_f32_16x16x32_bf16 v[66:69], v[164:167], v[208:211], v[66:69]
	s_setprio 0
	s_barrier
; #define PG8_STAGE(bufoff, gbase, voff) do { _Pragma("unroll") for (int _i = 0; _i < 2; ++_i) \
;         __builtin_amdgcn_global_load_lds((const unsigned*)((const char*)(gbase) + (voff)[_i]), (PG8_LAS unsigned*)(lds + (bufoff) + ldsw + _i * 8192), 16, 0, 0); } while (0)
; #define PG8_LDA(dst, b, h) do { _Pragma("unroll") for (int m = 0; m < 4; ++m) _Pragma("unroll") for (int k = 0; k < 2; ++k) dst[m][k] = *(const PG8_LAS bf16x8*)(lds + PG8_SA(b, h) + aoff + m * 2048 + k * 1024); } while (0)
; #define PG8_MMA(ai, bj, At, Bt) do { __builtin_amdgcn_s_setprio(1); _Pragma("unroll") for (int m = 0; m < 4; ++m) _Pragma("unroll") for (int n = 0; n < 2; ++n) _Pragma("unroll") for (int k = 0; k < 2; ++k) \
;         acc[ai][bj][m][n] = __builtin_amdgcn_mfma_f32_16x16x32_bf16(Bt[n][k], At[m][k], acc[ai][bj][m][n], 0, 0, 0); __builtin_amdgcn_s_setprio(0); } while (0)
; #define PG8_WAIT_V(n) asm volatile("s_waitcnt vmcnt(" #n ")" ::: "memory")
; #define PG8_WAIT_L(n) asm volatile("s_waitcnt lgkmcnt(" #n ")" ::: "memory")
; #define PG8_BAR __builtin_amdgcn_s_barrier()
; #define PG8_SCHED __builtin_amdgcn_sched_barrier(0)
; template <class Epi, class Sched, bool ALIGN_EPI = false, bool SP2 = false>
; __device__ __forceinline__ void gemm_phase(PG8_LAS unsigned char* lds, const Gemm g, const Sched& S, const Epi& E) {
;     ...
;             PG8_LDA(At, 1, 1); PG8_STAGE(PG8_SB(1, 0), b3, voffB); PG8_STAGE(PG8_SB(1, 1), b3 + hstep, voffB); PG8_STAGE(PG8_SA(1, 0), a3, voffA);
;             PG8_WAIT_V(8); PG8_WAIT_L(0); PG8_BAR; PG8_MMA(1, 0, At, B0); PG8_MMA(1, 1, At, B1); PG8_BAR; PG8_SCHED;
	s_add_i32 s50, s50, s35
	v_lshl_add_u64 v[184:185], v[184:185], 0, s[60:61]
	s_mov_b32 m0, s50
	ds_read_b128 v[168:171], v175 offset:49152
	ds_read_b128 v[176:179], v175 offset:50176
	ds_read_b128 v[180:183], v175 offset:51200
	ds_read_b128 v[192:195], v175 offset:52224
	ds_read_b128 v[196:199], v175 offset:53248
	ds_read_b128 v[200:203], v175 offset:54272
	ds_read_b128 v[204:207], v175 offset:55296
	ds_read_b128 v[208:211], v175 offset:56320
	global_load_lds_dwordx4 v[184:185], off
	s_add_i32 m0, s50, 0x2000
	s_add_u32 s76, s80, 0x40080
	v_lshl_add_u64 v[184:185], v[188:189], 0, s[60:61]
	s_addc_u32 s77, s81, 0
	s_add_i32 s50, s51, s35
	global_load_lds_dwordx4 v[184:185], off
	v_lshl_add_u64 v[184:185], s[76:77], 0, v[0:1]
	s_mov_b32 m0, s50
	s_nop 0
	global_load_lds_dwordx4 v[184:185], off
	v_lshl_add_u64 v[184:185], s[76:77], 0, v[130:131]
	s_add_i32 m0, s50, 0x2000
	s_nop 0
	global_load_lds_dwordx4 v[184:185], off
	v_lshl_add_u64 v[184:185], v[190:191], 0, s[60:61]
	s_mov_b32 m0, s87
	s_nop 0
	global_load_lds_dwordx4 v[184:185], off
	v_lshl_add_u64 v[184:185], v[212:213], 0, s[60:61]
	s_mov_b32 m0, s90
	s_nop 0
	global_load_lds_dwordx4 v[184:185], off
	s_waitcnt vmcnt(8)
	s_waitcnt lgkmcnt(0)
	s_barrier
	s_setprio 1
	s_waitcnt lgkmcnt(0)
	v_mfma_f32_16x16x32_bf16 v[62:65], v[136:139], v[168:171], v[62:65]
	v_mfma_f32_16x16x32_bf16 v[58:61], v[144:147], v[168:171], v[58:61]
	v_mfma_f32_16x16x32_bf16 v[46:49], v[136:139], v[180:183], v[46:49]
	v_mfma_f32_16x16x32_bf16 v[42:45], v[144:147], v[180:183], v[42:45]
	v_mfma_f32_16x16x32_bf16 v[30:33], v[136:139], v[196:199], v[30:33]
	v_mfma_f32_16x16x32_bf16 v[26:29], v[144:147], v[196:199], v[26:29]
	v_mfma_f32_16x16x32_bf16 v[14:17], v[136:139], v[204:207], v[14:17]
	v_mfma_f32_16x16x32_bf16 v[10:13], v[144:147], v[204:207], v[10:13]
	v_mfma_f32_16x16x32_bf16 v[62:65], v[140:143], v[176:179], v[62:65]
	v_mfma_f32_16x16x32_bf16 v[58:61], v[148:151], v[176:179], v[58:61]
	v_mfma_f32_16x16x32_bf16 v[46:49], v[140:143], v[192:195], v[46:49]
	v_mfma_f32_16x16x32_bf16 v[42:45], v[148:151], v[192:195], v[42:45]
	v_mfma_f32_16x16x32_bf16 v[30:33], v[140:143], v[200:203], v[30:33]
	v_mfma_f32_16x16x32_bf16 v[26:29], v[148:151], v[200:203], v[26:29]
	v_mfma_f32_16x16x32_bf16 v[14:17], v[140:143], v[208:211], v[14:17]
	v_mfma_f32_16x16x32_bf16 v[10:13], v[148:151], v[208:211], v[10:13]
	s_setprio 0
	s_setprio 1
	v_mfma_f32_16x16x32_bf16 v[54:57], v[152:155], v[168:171], v[54:57]
	v_mfma_f32_16x16x32_bf16 v[50:53], v[160:163], v[168:171], v[50:53]
	v_mfma_f32_16x16x32_bf16 v[38:41], v[152:155], v[180:183], v[38:41]
	v_mfma_f32_16x16x32_bf16 v[34:37], v[160:163], v[180:183], v[34:37]
	v_mfma_f32_16x16x32_bf16 v[22:25], v[152:155], v[196:199], v[22:25]
	v_mfma_f32_16x16x32_bf16 v[18:21], v[160:163], v[196:199], v[18:21]
	v_mfma_f32_16x16x32_bf16 v[6:9], v[152:155], v[204:207], v[6:9]
	v_mfma_f32_16x16x32_bf16 v[2:5], v[160:163], v[204:207], v[2:5]
	v_mfma_f32_16x16x32_bf16 v[54:57], v[156:159], v[176:179], v[54:57]
	v_mfma_f32_16x16x32_bf16 v[50:53], v[164:167], v[176:179], v[50:53]
	v_mfma_f32_16x16x32_bf16 v[38:41], v[156:159], v[192:195], v[38:41]
	v_mfma_f32_16x16x32_bf16 v[34:37], v[164:167], v[192:195], v[34:37]
	v_mfma_f32_16x16x32_bf16 v[22:25], v[156:159], v[200:203], v[22:25]
	v_mfma_f32_16x16x32_bf16 v[18:21], v[164:167], v[200:203], v[18:21]
	v_mfma_f32_16x16x32_bf16 v[6:9], v[156:159], v[208:211], v[6:9]
	v_mfma_f32_16x16x32_bf16 v[2:5], v[164:167], v[208:211], v[2:5]
	s_setprio 0
	s_barrier
	s_add_i32 s56, s56, 2
	s_add_u32 s54, s54, 0x100
	s_addc_u32 s55, s55, 0
	s_cmp_gt_u32 s56, 13
	s_mov_b64 s[76:77], s[78:79]
	s_cbranch_scc0 .LBB0_1263

; #define PG8_STAGE(bufoff, gbase, voff) do { _Pragma("unroll") for (int _i = 0; _i < 2; ++_i) \
;         __builtin_amdgcn_global_load_lds((const unsigned*)((const char*)(gbase) + (voff)[_i]), (PG8_LAS unsigned*)(lds + (bufoff) + ldsw + _i * 8192), 16, 0, 0); } while (0)
; #define PG8_LDA(dst, b, h) do { _Pragma("unroll") for (int m = 0; m < 4; ++m) _Pragma("unroll") for (int k = 0; k < 2; ++k) dst[m][k] = *(const PG8_LAS bf16x8*)(lds + PG8_SA(b, h) + aoff + m * 2048 + k * 1024); } while (0)
; #define PG8_LDB(dst, b, h) do { _Pragma("unroll") for (int n = 0; n < 2; ++n) _Pragma("unroll") for (int k = 0; k < 2; ++k) dst[n][k] = *(const PG8_LAS bf16x8*)(lds + PG8_SB(b, h) + boff + n * 2048 + k * 1024); } while (0)
; template <class Epi, class Sched, bool ALIGN_EPI = false, bool SP2 = false>
; __device__ __forceinline__ void gemm_phase(PG8_LAS unsigned char* lds, const Gemm g, const Sched& S, const Epi& E) {
;     ...
;         const bool has_next = S.next(ui + 1, nxt);
;         const char* nA = has_next ? (const char*)g.A + (size_t)nxt.pm * tstep : cA; const char* nB = has_next ? (const char*)g.Bt + (size_t)nxt.pn * tstep : cB;
;         for (int t = 0; t < nt; t += 2) {
;             const bool last = (t == nt - 2);
;             const char* a1 = cA + (size_t)(t + 1) * kstep;
;             const char* a2 = last ? nA : cA + (size_t)(t + 2) * kstep; const char* b2 = last ? nB : cB + (size_t)(t + 2) * kstep;
;             const char* a3 = a2 + kstep; const char* b3 = b2 + kstep;
;             if (last && has_next) S.a_ready(nxt);
;             if constexpr (SP2) {
;             PG8_LDB(B0, 0, 0); PG8_LDB(B1, 0, 1); PG8_SCHED; PG8_LDA(At, 0, 0); PG8_STAGE(PG8_SA(1, 1), a1 + hstep, voffA);
;             PG8_WAIT_V(8); PG8_WAIT_L(0); PG8_BAR; PG8_MMA(0, 0, At, B0); PG8_MMA(0, 1, At, B1); PG8_BAR; PG8_SCHED;
;             PG8_LDA(At, 0, 1); PG8_STAGE(PG8_SB(0, 0), b2, voffB); PG8_STAGE(PG8_SB(0, 1), b2 + hstep, voffB); PG8_STAGE(PG8_SA(0, 0), a2, voffA);
;             PG8_WAIT_V(8); PG8_WAIT_L(0); PG8_BAR; PG8_MMA(1, 0, At, B0); PG8_MMA(1, 1, At, B1); PG8_BAR; PG8_SCHED;
;     ...
;         for (int a = 0; a < 2; ++a)
; #pragma unroll
;             for (int b = 0; b < 2; ++b)
; #pragma unroll
;                 for (int m = 0; m < 4; ++m)
; #pragma unroll
;                     for (int n = 0; n < 2; ++n) acc[a][b][m][n] = (f32x4){0.f, 0.f, 0.f, 0.f};
.LBB0_1346:
	s_ashr_i32 s81, s80, 31
	s_lshl_b64 s[52:53], s[80:81], 19
	s_add_u32 s82, s42, s52
	s_addc_u32 s83, s43, s53
	s_and_b64 s[52:53], s[10:11], exec
	s_cselect_b32 s81, s83, s1
	s_cselect_b32 s52, s82, s0
	s_ashr_i32 s79, s78, 31
	s_lshl_b64 s[54:55], s[78:79], 19
	s_add_u32 s86, s64, s54
	s_addc_u32 s87, s94, s55
	s_and_b64 s[54:55], s[10:11], exec
	s_cselect_b32 s53, s87, s85
	s_cselect_b32 s79, s86, s84
	s_add_u32 s0, s0, 0x40080
	s_addc_u32 s1, s1, 0
	s_add_u32 s54, s84, 0x100
	s_addc_u32 s55, s85, 0
	s_mov_b32 s56, -2
	s_waitcnt vmcnt(0)
	s_add_u32 s50, s0, 0xfffc0080
	s_addc_u32 s51, s1, -1
	s_add_i32 s57, 0, 0x10000
	s_cmp_eq_u32 s56, 12
	s_cselect_b32 vcc_hi, s81, s51
	s_cselect_b32 vcc_lo, s52, s50
	s_cselect_b32 s85, s53, s55
	s_cselect_b32 s84, s79, s54
	s_add_i32 s66, 0, 0x14000
	v_add_u32_e32 v142, s57, v187
	v_add_u32_e32 v172, s66, v187
	ds_read_b128 v[130:133], v142
	ds_read_b128 v[134:137], v142 offset:1024
	ds_read_b128 v[138:141], v142 offset:2048
	ds_read_b128 v[142:145], v142 offset:3072
	ds_read_b128 v[146:149], v172
	ds_read_b128 v[150:153], v172 offset:1024
	ds_read_b128 v[168:171], v172 offset:2048
	ds_read_b128 v[172:175], v172 offset:3072
	v_lshl_add_u64 v[184:185], s[0:1], 0, v[164:165]
	s_add_i32 m0, s96, 0xc000
	ds_read_b128 v[176:179], v239
	ds_read_b128 v[180:183], v239 offset:1024
	ds_read_b128 v[192:195], v239 offset:2048
	ds_read_b128 v[196:199], v239 offset:3072
	ds_read_b128 v[200:203], v239 offset:4096
	ds_read_b128 v[204:207], v239 offset:5120
	ds_read_b128 v[208:211], v239 offset:6144
	ds_read_b128 v[212:215], v239 offset:7168
	global_load_lds_dwordx4 v[184:185], off
	v_lshl_add_u64 v[184:185], s[0:1], 0, v[166:167]
	s_add_i32 m0, s96, 0xe000
	s_nop 0
	global_load_lds_dwordx4 v[184:185], off
	s_cmp_lg_u32 s100, 0
	s_cbranch_scc1 .Lpe_skipP_up_0
	s_waitcnt vmcnt(8)
.Lpe_skipP_up_0:
	s_waitcnt lgkmcnt(0)
	s_barrier
	s_setprio 1
	s_waitcnt lgkmcnt(0)
	v_mfma_f32_16x16x32_bf16 v[102:105], v[130:133], v[176:179], 0
	v_mfma_f32_16x16x32_bf16 v[62:65], v[138:141], v[176:179], 0
	v_mfma_f32_16x16x32_bf16 v[126:129], v[130:133], v[192:195], 0
	v_mfma_f32_16x16x32_bf16 v[54:57], v[138:141], v[192:195], 0
	v_mfma_f32_16x16x32_bf16 v[122:125], v[130:133], v[200:203], 0
	v_mfma_f32_16x16x32_bf16 v[50:53], v[138:141], v[200:203], 0
	v_mfma_f32_16x16x32_bf16 v[114:117], v[130:133], v[208:211], 0
	v_mfma_f32_16x16x32_bf16 v[42:45], v[138:141], v[208:211], 0
	v_mfma_f32_16x16x32_bf16 v[102:105], v[134:137], v[180:183], v[102:105]
	v_mfma_f32_16x16x32_bf16 v[62:65], v[142:145], v[180:183], v[62:65]
	v_mfma_f32_16x16x32_bf16 v[126:129], v[134:137], v[196:199], v[126:129]
	v_mfma_f32_16x16x32_bf16 v[54:57], v[142:145], v[196:199], v[54:57]
	v_mfma_f32_16x16x32_bf16 v[122:125], v[134:137], v[204:207], v[122:125]
	v_mfma_f32_16x16x32_bf16 v[50:53], v[142:145], v[204:207], v[50:53]
	v_mfma_f32_16x16x32_bf16 v[114:117], v[134:137], v[212:215], v[114:117]
	v_mfma_f32_16x16x32_bf16 v[42:45], v[142:145], v[212:215], v[42:45]
	s_setprio 0
	s_setprio 1
	v_mfma_f32_16x16x32_bf16 v[98:101], v[146:149], v[176:179], 0
	v_mfma_f32_16x16x32_bf16 v[58:61], v[168:171], v[176:179], 0
	v_mfma_f32_16x16x32_bf16 v[118:121], v[146:149], v[192:195], 0
	v_mfma_f32_16x16x32_bf16 v[46:49], v[168:171], v[192:195], 0
	v_mfma_f32_16x16x32_bf16 v[110:113], v[146:149], v[200:203], 0
	v_mfma_f32_16x16x32_bf16 v[38:41], v[168:171], v[200:203], 0
	v_mfma_f32_16x16x32_bf16 v[106:109], v[146:149], v[208:211], 0
	v_mfma_f32_16x16x32_bf16 v[34:37], v[168:171], v[208:211], 0
	v_mfma_f32_16x16x32_bf16 v[98:101], v[150:153], v[180:183], v[98:101]
	v_mfma_f32_16x16x32_bf16 v[58:61], v[172:175], v[180:183], v[58:61]
	v_mfma_f32_16x16x32_bf16 v[118:121], v[150:153], v[196:199], v[118:121]
	v_mfma_f32_16x16x32_bf16 v[46:49], v[172:175], v[196:199], v[46:49]
	v_mfma_f32_16x16x32_bf16 v[110:113], v[150:153], v[204:207], v[110:113]
	v_mfma_f32_16x16x32_bf16 v[38:41], v[172:175], v[204:207], v[38:41]
	v_mfma_f32_16x16x32_bf16 v[106:109], v[150:153], v[212:215], v[106:109]
	v_mfma_f32_16x16x32_bf16 v[34:37], v[172:175], v[212:215], v[34:37]
	s_setprio 0
	s_barrier
	s_add_i32 s50, s57, s95
	v_lshl_add_u64 v[184:185], s[84:85], 0, v[0:1]
	s_mov_b32 m0, s50
	ds_read_b128 v[176:179], v239 offset:16384
	ds_read_b128 v[180:183], v239 offset:17408
	ds_read_b128 v[192:195], v239 offset:18432
	ds_read_b128 v[196:199], v239 offset:19456
	ds_read_b128 v[200:203], v239 offset:20480
	ds_read_b128 v[204:207], v239 offset:21504
	ds_read_b128 v[208:211], v239 offset:22528
	ds_read_b128 v[212:215], v239 offset:23552
	global_load_lds_dwordx4 v[184:185], off
	s_add_i32 m0, s50, 0x2000
	s_add_u32 s50, s84, 0x40000
	v_lshl_add_u64 v[188:189], s[84:85], 0, v[154:155]
	s_addc_u32 s51, s85, 0
	s_add_i32 s57, s66, s95
	global_load_lds_dwordx4 v[188:189], off
	v_lshl_add_u64 v[190:191], s[50:51], 0, v[0:1]
	s_mov_b32 m0, s57
	v_lshl_add_u64 v[216:217], vcc, 0, v[156:157]
	global_load_lds_dwordx4 v[190:191], off
	v_lshl_add_u64 v[190:191], s[50:51], 0, v[154:155]
	s_add_i32 m0, s57, 0x2000
	s_nop 0
	global_load_lds_dwordx4 v[190:191], off
	v_lshl_add_u64 v[190:191], vcc, 0, v[158:159]
	s_mov_b32 m0, s96
	s_nop 0
	global_load_lds_dwordx4 v[190:191], off
	s_mov_b32 m0, s97
	s_nop 0
	global_load_lds_dwordx4 v[216:217], off
	s_cmp_lg_u32 s100, 0
	s_cbranch_scc1 .Lpe_skipP_up_1
	s_waitcnt vmcnt(8)
; #define PG8_STAGE(bufoff, gbase, voff) do { _Pragma("unroll") for (int _i = 0; _i < 2; ++_i) \
;         __builtin_amdgcn_global_load_lds((const unsigned*)((const char*)(gbase) + (voff)[_i]), (PG8_LAS unsigned*)(lds + (bufoff) + ldsw + _i * 8192), 16, 0, 0); } while (0)
; #define PG8_LDA(dst, b, h) do { _Pragma("unroll") for (int m = 0; m < 4; ++m) _Pragma("unroll") for (int k = 0; k < 2; ++k) dst[m][k] = *(const PG8_LAS bf16x8*)(lds + PG8_SA(b, h) + aoff + m * 2048 + k * 1024); } while (0)
; #define PG8_LDB(dst, b, h) do { _Pragma("unroll") for (int n = 0; n < 2; ++n) _Pragma("unroll") for (int k = 0; k < 2; ++k) dst[n][k] = *(const PG8_LAS bf16x8*)(lds + PG8_SB(b, h) + boff + n * 2048 + k * 1024); } while (0)
; #define PG8_MMA(ai, bj, At, Bt) do { __builtin_amdgcn_s_setprio(1); _Pragma("unroll") for (int m = 0; m < 4; ++m) _Pragma("unroll") for (int n = 0; n < 2; ++n) _Pragma("unroll") for (int k = 0; k < 2; ++k) \
;         acc[ai][bj][m][n] = __builtin_amdgcn_mfma_f32_16x16x32_bf16(Bt[n][k], At[m][k], acc[ai][bj][m][n], 0, 0, 0); __builtin_amdgcn_s_setprio(0); } while (0)
; #define PG8_WAIT_V(n) asm volatile("s_waitcnt vmcnt(" #n ")" ::: "memory")
; #define PG8_WAIT_L(n) asm volatile("s_waitcnt lgkmcnt(" #n ")" ::: "memory")
; #define PG8_BAR __builtin_amdgcn_s_barrier()
; #define PG8_SCHED __builtin_amdgcn_sched_barrier(0)
; template <class Epi, class Sched, bool ALIGN_EPI = false, bool SP2 = false>
; __device__ __forceinline__ void gemm_phase(PG8_LAS unsigned char* lds, const Gemm g, const Sched& S, const Epi& E) {
;     ...
;             PG8_WAIT_V(8); PG8_WAIT_L(0); PG8_BAR; PG8_MMA(1, 0, At, B0); PG8_MMA(1, 1, At, B1); PG8_BAR; PG8_SCHED;
;             PG8_LDB(B0, 1, 0); PG8_LDB(B1, 1, 1); PG8_SCHED; PG8_LDA(At, 1, 0); PG8_STAGE(PG8_SA(0, 1), a2 + hstep, voffA);
;             PG8_WAIT_V(8); PG8_WAIT_L(0); PG8_BAR; PG8_MMA(0, 0, At, B0); PG8_MMA(0, 1, At, B1); PG8_BAR; PG8_SCHED;
.Lpe_skipP_up_1:
	s_mov_b32 s100, 0
	s_waitcnt lgkmcnt(0)
	s_barrier
	s_setprio 1
	s_waitcnt lgkmcnt(0)
	v_mfma_f32_16x16x32_bf16 v[94:97], v[130:133], v[176:179], 0
	v_mfma_f32_16x16x32_bf16 v[30:33], v[138:141], v[176:179], 0
	v_mfma_f32_16x16x32_bf16 v[86:89], v[130:133], v[192:195], 0
	v_mfma_f32_16x16x32_bf16 v[22:25], v[138:141], v[192:195], 0
	v_mfma_f32_16x16x32_bf16 v[82:85], v[130:133], v[200:203], 0
	v_mfma_f32_16x16x32_bf16 v[18:21], v[138:141], v[200:203], 0
	v_mfma_f32_16x16x32_bf16 v[74:77], v[130:133], v[208:211], 0
	v_mfma_f32_16x16x32_bf16 v[10:13], v[138:141], v[208:211], 0
	v_mfma_f32_16x16x32_bf16 v[94:97], v[134:137], v[180:183], v[94:97]
	v_mfma_f32_16x16x32_bf16 v[30:33], v[142:145], v[180:183], v[30:33]
	v_mfma_f32_16x16x32_bf16 v[86:89], v[134:137], v[196:199], v[86:89]
	v_mfma_f32_16x16x32_bf16 v[22:25], v[142:145], v[196:199], v[22:25]
	v_mfma_f32_16x16x32_bf16 v[82:85], v[134:137], v[204:207], v[82:85]
	v_mfma_f32_16x16x32_bf16 v[18:21], v[142:145], v[204:207], v[18:21]
	v_mfma_f32_16x16x32_bf16 v[74:77], v[134:137], v[212:215], v[74:77]
	v_mfma_f32_16x16x32_bf16 v[10:13], v[142:145], v[212:215], v[10:13]
	s_setprio 0
	s_setprio 1
	v_mfma_f32_16x16x32_bf16 v[90:93], v[146:149], v[176:179], 0
	v_mfma_f32_16x16x32_bf16 v[26:29], v[168:171], v[176:179], 0
	v_mfma_f32_16x16x32_bf16 v[78:81], v[146:149], v[192:195], 0
	v_mfma_f32_16x16x32_bf16 v[14:17], v[168:171], v[192:195], 0
	v_mfma_f32_16x16x32_bf16 v[70:73], v[146:149], v[200:203], 0
	v_mfma_f32_16x16x32_bf16 v[6:9], v[168:171], v[200:203], 0
	v_mfma_f32_16x16x32_bf16 v[66:69], v[146:149], v[208:211], 0
	v_mfma_f32_16x16x32_bf16 v[2:5], v[168:171], v[208:211], 0
	v_mfma_f32_16x16x32_bf16 v[90:93], v[150:153], v[180:183], v[90:93]
	v_mfma_f32_16x16x32_bf16 v[26:29], v[172:175], v[180:183], v[26:29]
	v_mfma_f32_16x16x32_bf16 v[78:81], v[150:153], v[196:199], v[78:81]
	v_mfma_f32_16x16x32_bf16 v[14:17], v[172:175], v[196:199], v[14:17]
	v_mfma_f32_16x16x32_bf16 v[70:73], v[150:153], v[204:207], v[70:73]
	v_mfma_f32_16x16x32_bf16 v[6:9], v[172:175], v[204:207], v[6:9]
	v_mfma_f32_16x16x32_bf16 v[66:69], v[150:153], v[212:215], v[66:69]
	v_mfma_f32_16x16x32_bf16 v[2:5], v[172:175], v[212:215], v[2:5]
	s_setprio 0
	s_barrier
	s_add_i32 s57, 0, 0x18000
	s_add_i32 s66, 0, 0x1c000
	v_add_u32_e32 v142, s57, v187
	v_add_u32_e32 v172, s66, v187
	ds_read_b128 v[130:133], v142
	ds_read_b128 v[134:137], v142 offset:1024
	ds_read_b128 v[138:141], v142 offset:2048
	ds_read_b128 v[142:145], v142 offset:3072
	ds_read_b128 v[146:149], v172
	ds_read_b128 v[150:153], v172 offset:1024
	ds_read_b128 v[168:171], v172 offset:2048
	ds_read_b128 v[172:175], v172 offset:3072
	s_add_u32 s50, vcc_lo, 0x40000
	s_addc_u32 s51, vcc_hi, 0
	s_mov_b32 m0, s62
	v_lshl_add_u64 v[218:219], s[50:51], 0, v[158:159]
	ds_read_b128 v[176:179], v239 offset:32768
	ds_read_b128 v[180:183], v239 offset:33792
	ds_read_b128 v[192:195], v239 offset:34816
	ds_read_b128 v[196:199], v239 offset:35840
	ds_read_b128 v[200:203], v239 offset:36864
	ds_read_b128 v[204:207], v239 offset:37888
	ds_read_b128 v[208:211], v239 offset:38912
	ds_read_b128 v[212:215], v239 offset:39936
	global_load_lds_dwordx4 v[218:219], off
	v_lshl_add_u64 v[218:219], s[50:51], 0, v[156:157]
	s_mov_b32 m0, s63
	s_nop 0
	global_load_lds_dwordx4 v[218:219], off
	s_waitcnt vmcnt(8)
	s_waitcnt lgkmcnt(0)
	s_barrier
	s_setprio 1
	s_waitcnt lgkmcnt(0)
	v_mfma_f32_16x16x32_bf16 v[102:105], v[130:133], v[176:179], v[102:105]
	v_mfma_f32_16x16x32_bf16 v[62:65], v[138:141], v[176:179], v[62:65]
	v_mfma_f32_16x16x32_bf16 v[126:129], v[130:133], v[192:195], v[126:129]
	v_mfma_f32_16x16x32_bf16 v[54:57], v[138:141], v[192:195], v[54:57]
	v_mfma_f32_16x16x32_bf16 v[122:125], v[130:133], v[200:203], v[122:125]
	v_mfma_f32_16x16x32_bf16 v[50:53], v[138:141], v[200:203], v[50:53]
	v_mfma_f32_16x16x32_bf16 v[114:117], v[130:133], v[208:211], v[114:117]
	v_mfma_f32_16x16x32_bf16 v[42:45], v[138:141], v[208:211], v[42:45]
	v_mfma_f32_16x16x32_bf16 v[102:105], v[134:137], v[180:183], v[102:105]
	v_mfma_f32_16x16x32_bf16 v[62:65], v[142:145], v[180:183], v[62:65]
	v_mfma_f32_16x16x32_bf16 v[126:129], v[134:137], v[196:199], v[126:129]
	v_mfma_f32_16x16x32_bf16 v[54:57], v[142:145], v[196:199], v[54:57]
	v_mfma_f32_16x16x32_bf16 v[122:125], v[134:137], v[204:207], v[122:125]
	v_mfma_f32_16x16x32_bf16 v[50:53], v[142:145], v[204:207], v[50:53]
	v_mfma_f32_16x16x32_bf16 v[114:117], v[134:137], v[212:215], v[114:117]
	v_mfma_f32_16x16x32_bf16 v[42:45], v[142:145], v[212:215], v[42:45]
	s_setprio 0
	s_setprio 1
	v_mfma_f32_16x16x32_bf16 v[98:101], v[146:149], v[176:179], v[98:101]
	v_mfma_f32_16x16x32_bf16 v[58:61], v[168:171], v[176:179], v[58:61]
	v_mfma_f32_16x16x32_bf16 v[118:121], v[146:149], v[192:195], v[118:121]
	v_mfma_f32_16x16x32_bf16 v[46:49], v[168:171], v[192:195], v[46:49]
	v_mfma_f32_16x16x32_bf16 v[110:113], v[146:149], v[200:203], v[110:113]
	v_mfma_f32_16x16x32_bf16 v[38:41], v[168:171], v[200:203], v[38:41]
	v_mfma_f32_16x16x32_bf16 v[106:109], v[146:149], v[208:211], v[106:109]
	v_mfma_f32_16x16x32_bf16 v[34:37], v[168:171], v[208:211], v[34:37]
	v_mfma_f32_16x16x32_bf16 v[98:101], v[150:153], v[180:183], v[98:101]
	v_mfma_f32_16x16x32_bf16 v[58:61], v[172:175], v[180:183], v[58:61]
	v_mfma_f32_16x16x32_bf16 v[118:121], v[150:153], v[196:199], v[118:121]
	v_mfma_f32_16x16x32_bf16 v[46:49], v[172:175], v[196:199], v[46:49]
	v_mfma_f32_16x16x32_bf16 v[110:113], v[150:153], v[204:207], v[110:113]
	v_mfma_f32_16x16x32_bf16 v[38:41], v[172:175], v[204:207], v[38:41]
	v_mfma_f32_16x16x32_bf16 v[106:109], v[150:153], v[212:215], v[106:109]
	v_mfma_f32_16x16x32_bf16 v[34:37], v[172:175], v[212:215], v[34:37]
	s_setprio 0
	s_barrier
; #define PG8_STAGE(bufoff, gbase, voff) do { _Pragma("unroll") for (int _i = 0; _i < 2; ++_i) \
;         __builtin_amdgcn_global_load_lds((const unsigned*)((const char*)(gbase) + (voff)[_i]), (PG8_LAS unsigned*)(lds + (bufoff) + ldsw + _i * 8192), 16, 0, 0); } while (0)
; #define PG8_LDA(dst, b, h) do { _Pragma("unroll") for (int m = 0; m < 4; ++m) _Pragma("unroll") for (int k = 0; k < 2; ++k) dst[m][k] = *(const PG8_LAS bf16x8*)(lds + PG8_SA(b, h) + aoff + m * 2048 + k * 1024); } while (0)
; #define PG8_MMA(ai, bj, At, Bt) do { __builtin_amdgcn_s_setprio(1); _Pragma("unroll") for (int m = 0; m < 4; ++m) _Pragma("unroll") for (int n = 0; n < 2; ++n) _Pragma("unroll") for (int k = 0; k < 2; ++k) \
;         acc[ai][bj][m][n] = __builtin_amdgcn_mfma_f32_16x16x32_bf16(Bt[n][k], At[m][k], acc[ai][bj][m][n], 0, 0, 0); __builtin_amdgcn_s_setprio(0); } while (0)
; #define PG8_WAIT_V(n) asm volatile("s_waitcnt vmcnt(" #n ")" ::: "memory")
; #define PG8_WAIT_L(n) asm volatile("s_waitcnt lgkmcnt(" #n ")" ::: "memory")
; #define PG8_BAR __builtin_amdgcn_s_barrier()
; #define PG8_SCHED __builtin_amdgcn_sched_barrier(0)
; template <class Epi, class Sched, bool ALIGN_EPI = false, bool SP2 = false>
; __device__ __forceinline__ void gemm_phase(PG8_LAS unsigned char* lds, const Gemm g, const Sched& S, const Epi& E) {
;     ...
;             PG8_LDA(At, 1, 1); PG8_STAGE(PG8_SB(1, 0), b3, voffB); PG8_STAGE(PG8_SB(1, 1), b3 + hstep, voffB); PG8_STAGE(PG8_SA(1, 0), a3, voffA);
;             PG8_WAIT_V(8); PG8_WAIT_L(0); PG8_BAR; PG8_MMA(1, 0, At, B0); PG8_MMA(1, 1, At, B1); PG8_BAR; PG8_SCHED;
	s_add_i32 s50, s57, s95
	v_lshl_add_u64 v[184:185], v[184:185], 0, s[60:61]
	s_mov_b32 m0, s50
	ds_read_b128 v[176:179], v239 offset:49152
	ds_read_b128 v[180:183], v239 offset:50176
	ds_read_b128 v[192:195], v239 offset:51200
	ds_read_b128 v[196:199], v239 offset:52224
	ds_read_b128 v[200:203], v239 offset:53248
	ds_read_b128 v[204:207], v239 offset:54272
	ds_read_b128 v[208:211], v239 offset:55296
	ds_read_b128 v[212:215], v239 offset:56320
	global_load_lds_dwordx4 v[184:185], off
	s_add_i32 m0, s50, 0x2000
	s_add_u32 s50, s84, 0x40080
	v_lshl_add_u64 v[184:185], v[188:189], 0, s[60:61]
	s_addc_u32 s51, s85, 0
	s_add_i32 s57, s66, s95
	global_load_lds_dwordx4 v[184:185], off
	v_lshl_add_u64 v[184:185], s[50:51], 0, v[0:1]
	s_mov_b32 m0, s57
	s_nop 0
	global_load_lds_dwordx4 v[184:185], off
	v_lshl_add_u64 v[184:185], s[50:51], 0, v[154:155]
	s_add_i32 m0, s57, 0x2000
	s_nop 0
	global_load_lds_dwordx4 v[184:185], off
	v_lshl_add_u64 v[184:185], v[190:191], 0, s[60:61]
	s_mov_b32 m0, s25
	s_nop 0
	global_load_lds_dwordx4 v[184:185], off
	v_lshl_add_u64 v[184:185], v[216:217], 0, s[60:61]
	s_mov_b32 m0, s35
	s_nop 0
	global_load_lds_dwordx4 v[184:185], off
	s_waitcnt vmcnt(8)
	s_waitcnt lgkmcnt(0)
	s_barrier
	s_setprio 1
	s_waitcnt lgkmcnt(0)
	v_mfma_f32_16x16x32_bf16 v[94:97], v[130:133], v[176:179], v[94:97]
	v_mfma_f32_16x16x32_bf16 v[30:33], v[138:141], v[176:179], v[30:33]
	v_mfma_f32_16x16x32_bf16 v[86:89], v[130:133], v[192:195], v[86:89]
	v_mfma_f32_16x16x32_bf16 v[22:25], v[138:141], v[192:195], v[22:25]
	v_mfma_f32_16x16x32_bf16 v[82:85], v[130:133], v[200:203], v[82:85]
	v_mfma_f32_16x16x32_bf16 v[18:21], v[138:141], v[200:203], v[18:21]
	v_mfma_f32_16x16x32_bf16 v[74:77], v[130:133], v[208:211], v[74:77]
	v_mfma_f32_16x16x32_bf16 v[10:13], v[138:141], v[208:211], v[10:13]
	v_mfma_f32_16x16x32_bf16 v[94:97], v[134:137], v[180:183], v[94:97]
	v_mfma_f32_16x16x32_bf16 v[30:33], v[142:145], v[180:183], v[30:33]
	v_mfma_f32_16x16x32_bf16 v[86:89], v[134:137], v[196:199], v[86:89]
	v_mfma_f32_16x16x32_bf16 v[22:25], v[142:145], v[196:199], v[22:25]
	v_mfma_f32_16x16x32_bf16 v[82:85], v[134:137], v[204:207], v[82:85]
	v_mfma_f32_16x16x32_bf16 v[18:21], v[142:145], v[204:207], v[18:21]
	v_mfma_f32_16x16x32_bf16 v[74:77], v[134:137], v[212:215], v[74:77]
	v_mfma_f32_16x16x32_bf16 v[10:13], v[142:145], v[212:215], v[10:13]
	s_setprio 0
	s_setprio 1
	v_mfma_f32_16x16x32_bf16 v[90:93], v[146:149], v[176:179], v[90:93]
	v_mfma_f32_16x16x32_bf16 v[26:29], v[168:171], v[176:179], v[26:29]
	v_mfma_f32_16x16x32_bf16 v[78:81], v[146:149], v[192:195], v[78:81]
	v_mfma_f32_16x16x32_bf16 v[14:17], v[168:171], v[192:195], v[14:17]
	v_mfma_f32_16x16x32_bf16 v[70:73], v[146:149], v[200:203], v[70:73]
	v_mfma_f32_16x16x32_bf16 v[6:9], v[168:171], v[200:203], v[6:9]
	v_mfma_f32_16x16x32_bf16 v[66:69], v[146:149], v[208:211], v[66:69]
	v_mfma_f32_16x16x32_bf16 v[2:5], v[168:171], v[208:211], v[2:5]
	v_mfma_f32_16x16x32_bf16 v[90:93], v[150:153], v[180:183], v[90:93]
	v_mfma_f32_16x16x32_bf16 v[26:29], v[172:175], v[180:183], v[26:29]
	v_mfma_f32_16x16x32_bf16 v[78:81], v[150:153], v[196:199], v[78:81]
	v_mfma_f32_16x16x32_bf16 v[14:17], v[172:175], v[196:199], v[14:17]
	v_mfma_f32_16x16x32_bf16 v[70:73], v[150:153], v[204:207], v[70:73]
	v_mfma_f32_16x16x32_bf16 v[6:9], v[172:175], v[204:207], v[6:9]
	v_mfma_f32_16x16x32_bf16 v[66:69], v[150:153], v[212:215], v[66:69]
	v_mfma_f32_16x16x32_bf16 v[2:5], v[172:175], v[212:215], v[2:5]
	s_setprio 0
	s_barrier
	s_add_i32 s56, s56, 2
	s_add_u32 s0, s0, 0x100
	s_addc_u32 s1, s1, 0
	s_add_u32 s54, s54, 0x100
	s_addc_u32 s55, s55, 0
	s_cmp_gt_u32 s56, 13
	s_cbranch_scc0 .LBB0_1347

; #define PG8_STAGE(bufoff, gbase, voff) do { _Pragma("unroll") for (int _i = 0; _i < 2; ++_i) \
;         __builtin_amdgcn_global_load_lds((const unsigned*)((const char*)(gbase) + (voff)[_i]), (PG8_LAS unsigned*)(lds + (bufoff) + ldsw + _i * 8192), 16, 0, 0); } while (0)
; #define PG8_LDA(dst, b, h) do { _Pragma("unroll") for (int m = 0; m < 4; ++m) _Pragma("unroll") for (int k = 0; k < 2; ++k) dst[m][k] = *(const PG8_LAS bf16x8*)(lds + PG8_SA(b, h) + aoff + m * 2048 + k * 1024); } while (0)
; #define PG8_LDB(dst, b, h) do { _Pragma("unroll") for (int n = 0; n < 2; ++n) _Pragma("unroll") for (int k = 0; k < 2; ++k) dst[n][k] = *(const PG8_LAS bf16x8*)(lds + PG8_SB(b, h) + boff + n * 2048 + k * 1024); } while (0)
; #define PG8_MMA(ai, bj, At, Bt) do { __builtin_amdgcn_s_setprio(1); _Pragma("unroll") for (int m = 0; m < 4; ++m) _Pragma("unroll") for (int n = 0; n < 2; ++n) _Pragma("unroll") for (int k = 0; k < 2; ++k) \
;         acc[ai][bj][m][n] = __builtin_amdgcn_mfma_f32_16x16x32_bf16(Bt[n][k], At[m][k], acc[ai][bj][m][n], 0, 0, 0); __builtin_amdgcn_s_setprio(0); } while (0)
; template <class Epi, class Sched, bool ALIGN_EPI = false, bool SP2 = false>
; __device__ __forceinline__ void gemm_phase(PG8_LAS unsigned char* lds, const Gemm g, const Sched& S, const Epi& E) {
;     ...
;             const char* a2 = last ? nA : cA + (size_t)(t + 2) * kstep; const char* b2 = last ? nB : cB + (size_t)(t + 2) * kstep;
;             const char* a3 = a2 + kstep; const char* b3 = b2 + kstep;
;             if (last && has_next) S.a_ready(nxt);
;             if constexpr (SP2) {
;             PG8_LDB(B0, 0, 0); PG8_LDB(B1, 0, 1); PG8_SCHED; PG8_LDA(At, 0, 0); PG8_STAGE(PG8_SA(1, 1), a1 + hstep, voffA);
;             PG8_WAIT_V(8); PG8_WAIT_L(0); PG8_BAR; PG8_MMA(0, 0, At, B0); PG8_MMA(0, 1, At, B1); PG8_BAR; PG8_SCHED;
;             PG8_LDA(At, 0, 1); PG8_STAGE(PG8_SB(0, 0), b2, voffB); PG8_STAGE(PG8_SB(0, 1), b2 + hstep, voffB); PG8_STAGE(PG8_SA(0, 0), a2, voffA);
;             PG8_WAIT_V(8); PG8_WAIT_L(0); PG8_BAR; PG8_MMA(1, 0, At, B0); PG8_MMA(1, 1, At, B1); PG8_BAR; PG8_SCHED;
;     ...
;         for (int a = 0; a < 2; ++a)
; #pragma unroll
;             for (int b = 0; b < 2; ++b)
; #pragma unroll
;                 for (int m = 0; m < 4; ++m)
; #pragma unroll
;                     for (int n = 0; n < 2; ++n) acc[a][b][m][n] = (f32x4){0.f, 0.f, 0.f, 0.f};
.LBB0_1511:
	s_add_u32 s52, s74, 0x100
	s_addc_u32 s53, s75, 0
	s_mov_b32 s54, -2
	s_waitcnt lgkmcnt(0)
	s_waitcnt vmcnt(0)
	s_add_u32 s74, s72, 0x100
	s_addc_u32 s75, s73, 0
	s_add_i32 s50, 0, 0x10000
	s_cmp_eq_u32 s54, 40
	s_cselect_b32 s79, s9, s75
	s_cselect_b32 s78, s8, s74
	s_cselect_b32 s77, s71, s53
	s_cselect_b32 s76, s70, s52
	s_add_i32 s55, 0, 0x14000
	v_add_u32_e32 v148, s50, v173
	v_add_u32_e32 v164, s55, v173
	ds_read_b128 v[136:139], v148
	ds_read_b128 v[140:143], v148 offset:1024
	ds_read_b128 v[144:147], v148 offset:2048
	ds_read_b128 v[148:151], v148 offset:3072
	ds_read_b128 v[152:155], v164
	ds_read_b128 v[156:159], v164 offset:1024
	ds_read_b128 v[160:163], v164 offset:2048
	ds_read_b128 v[164:167], v164 offset:3072
	v_lshl_add_u64 v[184:185], s[72:73], 0, v[132:133]
	s_add_i32 m0, s62, 0xc000
	ds_read_b128 v[168:171], v175
	ds_read_b128 v[176:179], v175 offset:1024
	ds_read_b128 v[180:183], v175 offset:2048
	ds_read_b128 v[192:195], v175 offset:3072
	ds_read_b128 v[196:199], v175 offset:4096
	ds_read_b128 v[200:203], v175 offset:5120
	ds_read_b128 v[204:207], v175 offset:6144
	ds_read_b128 v[208:211], v175 offset:7168
	global_load_lds_dwordx4 v[184:185], off
	v_lshl_add_u64 v[184:185], s[72:73], 0, v[134:135]
	s_add_i32 m0, s62, 0xe000
	s_nop 0
	global_load_lds_dwordx4 v[184:185], off
	s_cmp_lg_u32 s100, 0
	s_cbranch_scc1 .Lpe_skipP_dn_0
	s_waitcnt vmcnt(8)
.Lpe_skipP_dn_0:
	s_waitcnt lgkmcnt(0)
	s_barrier
	s_setprio 1
	s_waitcnt lgkmcnt(0)
	v_mfma_f32_16x16x32_bf16 v[126:129], v[136:139], v[168:171], 0
	v_mfma_f32_16x16x32_bf16 v[122:125], v[144:147], v[168:171], 0
	v_mfma_f32_16x16x32_bf16 v[110:113], v[136:139], v[180:183], 0
	v_mfma_f32_16x16x32_bf16 v[106:109], v[144:147], v[180:183], 0
	v_mfma_f32_16x16x32_bf16 v[94:97], v[136:139], v[196:199], 0
	v_mfma_f32_16x16x32_bf16 v[90:93], v[144:147], v[196:199], 0
	v_mfma_f32_16x16x32_bf16 v[78:81], v[136:139], v[204:207], 0
	v_mfma_f32_16x16x32_bf16 v[74:77], v[144:147], v[204:207], 0
	v_mfma_f32_16x16x32_bf16 v[126:129], v[140:143], v[176:179], v[126:129]
	v_mfma_f32_16x16x32_bf16 v[122:125], v[148:151], v[176:179], v[122:125]
	v_mfma_f32_16x16x32_bf16 v[110:113], v[140:143], v[192:195], v[110:113]
	v_mfma_f32_16x16x32_bf16 v[106:109], v[148:151], v[192:195], v[106:109]
	v_mfma_f32_16x16x32_bf16 v[94:97], v[140:143], v[200:203], v[94:97]
	v_mfma_f32_16x16x32_bf16 v[90:93], v[148:151], v[200:203], v[90:93]
	v_mfma_f32_16x16x32_bf16 v[78:81], v[140:143], v[208:211], v[78:81]
	v_mfma_f32_16x16x32_bf16 v[74:77], v[148:151], v[208:211], v[74:77]
	s_setprio 0
	s_setprio 1
	v_mfma_f32_16x16x32_bf16 v[118:121], v[152:155], v[168:171], 0
	v_mfma_f32_16x16x32_bf16 v[114:117], v[160:163], v[168:171], 0
	v_mfma_f32_16x16x32_bf16 v[102:105], v[152:155], v[180:183], 0
	v_mfma_f32_16x16x32_bf16 v[98:101], v[160:163], v[180:183], 0
	v_mfma_f32_16x16x32_bf16 v[86:89], v[152:155], v[196:199], 0
	v_mfma_f32_16x16x32_bf16 v[82:85], v[160:163], v[196:199], 0
	v_mfma_f32_16x16x32_bf16 v[70:73], v[152:155], v[204:207], 0
	v_mfma_f32_16x16x32_bf16 v[66:69], v[160:163], v[204:207], 0
	v_mfma_f32_16x16x32_bf16 v[118:121], v[156:159], v[176:179], v[118:121]
	v_mfma_f32_16x16x32_bf16 v[114:117], v[164:167], v[176:179], v[114:117]
	v_mfma_f32_16x16x32_bf16 v[102:105], v[156:159], v[192:195], v[102:105]
	v_mfma_f32_16x16x32_bf16 v[98:101], v[164:167], v[192:195], v[98:101]
	v_mfma_f32_16x16x32_bf16 v[86:89], v[156:159], v[200:203], v[86:89]
	v_mfma_f32_16x16x32_bf16 v[82:85], v[164:167], v[200:203], v[82:85]
	v_mfma_f32_16x16x32_bf16 v[70:73], v[156:159], v[208:211], v[70:73]
	v_mfma_f32_16x16x32_bf16 v[66:69], v[164:167], v[208:211], v[66:69]
	s_setprio 0
	s_barrier
	s_add_i32 s50, s50, s35
	v_lshl_add_u64 v[184:185], s[76:77], 0, v[0:1]
	s_mov_b32 m0, s50
	ds_read_b128 v[168:171], v175 offset:16384
	ds_read_b128 v[176:179], v175 offset:17408
	ds_read_b128 v[180:183], v175 offset:18432
	ds_read_b128 v[192:195], v175 offset:19456
	ds_read_b128 v[196:199], v175 offset:20480
	ds_read_b128 v[200:203], v175 offset:21504
	ds_read_b128 v[204:207], v175 offset:22528
	ds_read_b128 v[208:211], v175 offset:23552
	global_load_lds_dwordx4 v[184:185], off
	s_add_i32 m0, s50, 0x2000
	s_add_u32 s50, s76, 0xb0000
	v_lshl_add_u64 v[188:189], s[76:77], 0, v[130:131]
	s_addc_u32 s51, s77, 0
	s_add_i32 s55, s55, s35
	global_load_lds_dwordx4 v[188:189], off
	v_lshl_add_u64 v[190:191], s[50:51], 0, v[0:1]
	s_mov_b32 m0, s55
	v_lshl_add_u64 v[212:213], s[78:79], 0, v[130:131]
	global_load_lds_dwordx4 v[190:191], off
	v_lshl_add_u64 v[190:191], s[50:51], 0, v[130:131]
	s_add_i32 m0, s55, 0x2000
	s_nop 0
	global_load_lds_dwordx4 v[190:191], off
	v_lshl_add_u64 v[190:191], s[78:79], 0, v[0:1]
	s_mov_b32 m0, s62
	s_nop 0
	global_load_lds_dwordx4 v[190:191], off
	s_mov_b32 m0, s63
	s_nop 0
	global_load_lds_dwordx4 v[212:213], off
	s_cmp_lg_u32 s100, 0
	s_cbranch_scc1 .Lpe_skipP_dn_1
	s_waitcnt vmcnt(8)
; #define PG8_STAGE(bufoff, gbase, voff) do { _Pragma("unroll") for (int _i = 0; _i < 2; ++_i) \
;         __builtin_amdgcn_global_load_lds((const unsigned*)((const char*)(gbase) + (voff)[_i]), (PG8_LAS unsigned*)(lds + (bufoff) + ldsw + _i * 8192), 16, 0, 0); } while (0)
; #define PG8_LDA(dst, b, h) do { _Pragma("unroll") for (int m = 0; m < 4; ++m) _Pragma("unroll") for (int k = 0; k < 2; ++k) dst[m][k] = *(const PG8_LAS bf16x8*)(lds + PG8_SA(b, h) + aoff + m * 2048 + k * 1024); } while (0)
; #define PG8_LDB(dst, b, h) do { _Pragma("unroll") for (int n = 0; n < 2; ++n) _Pragma("unroll") for (int k = 0; k < 2; ++k) dst[n][k] = *(const PG8_LAS bf16x8*)(lds + PG8_SB(b, h) + boff + n * 2048 + k * 1024); } while (0)
; #define PG8_MMA(ai, bj, At, Bt) do { __builtin_amdgcn_s_setprio(1); _Pragma("unroll") for (int m = 0; m < 4; ++m) _Pragma("unroll") for (int n = 0; n < 2; ++n) _Pragma("unroll") for (int k = 0; k < 2; ++k) \
;         acc[ai][bj][m][n] = __builtin_amdgcn_mfma_f32_16x16x32_bf16(Bt[n][k], At[m][k], acc[ai][bj][m][n], 0, 0, 0); __builtin_amdgcn_s_setprio(0); } while (0)
; #define PG8_WAIT_V(n) asm volatile("s_waitcnt vmcnt(" #n ")" ::: "memory")
; #define PG8_WAIT_L(n) asm volatile("s_waitcnt lgkmcnt(" #n ")" ::: "memory")
; #define PG8_BAR __builtin_amdgcn_s_barrier()
; #define PG8_SCHED __builtin_amdgcn_sched_barrier(0)
; template <class Epi, class Sched, bool ALIGN_EPI = false, bool SP2 = false>
; __device__ __forceinline__ void gemm_phase(PG8_LAS unsigned char* lds, const Gemm g, const Sched& S, const Epi& E) {
;     ...
;             PG8_WAIT_V(8); PG8_WAIT_L(0); PG8_BAR; PG8_MMA(1, 0, At, B0); PG8_MMA(1, 1, At, B1); PG8_BAR; PG8_SCHED;
;             PG8_LDB(B0, 1, 0); PG8_LDB(B1, 1, 1); PG8_SCHED; PG8_LDA(At, 1, 0); PG8_STAGE(PG8_SA(0, 1), a2 + hstep, voffA);
;             PG8_WAIT_V(8); PG8_WAIT_L(0); PG8_BAR; PG8_MMA(0, 0, At, B0); PG8_MMA(0, 1, At, B1); PG8_BAR; PG8_SCHED;
.Lpe_skipP_dn_1:
	s_mov_b32 s100, 0
	s_waitcnt lgkmcnt(0)
	s_barrier
	s_setprio 1
	s_waitcnt lgkmcnt(0)
	v_mfma_f32_16x16x32_bf16 v[62:65], v[136:139], v[168:171], 0
	v_mfma_f32_16x16x32_bf16 v[58:61], v[144:147], v[168:171], 0
	v_mfma_f32_16x16x32_bf16 v[46:49], v[136:139], v[180:183], 0
	v_mfma_f32_16x16x32_bf16 v[42:45], v[144:147], v[180:183], 0
	v_mfma_f32_16x16x32_bf16 v[30:33], v[136:139], v[196:199], 0
	v_mfma_f32_16x16x32_bf16 v[26:29], v[144:147], v[196:199], 0
	v_mfma_f32_16x16x32_bf16 v[14:17], v[136:139], v[204:207], 0
	v_mfma_f32_16x16x32_bf16 v[10:13], v[144:147], v[204:207], 0
	v_mfma_f32_16x16x32_bf16 v[62:65], v[140:143], v[176:179], v[62:65]
	v_mfma_f32_16x16x32_bf16 v[58:61], v[148:151], v[176:179], v[58:61]
	v_mfma_f32_16x16x32_bf16 v[46:49], v[140:143], v[192:195], v[46:49]
	v_mfma_f32_16x16x32_bf16 v[42:45], v[148:151], v[192:195], v[42:45]
	v_mfma_f32_16x16x32_bf16 v[30:33], v[140:143], v[200:203], v[30:33]
	v_mfma_f32_16x16x32_bf16 v[26:29], v[148:151], v[200:203], v[26:29]
	v_mfma_f32_16x16x32_bf16 v[14:17], v[140:143], v[208:211], v[14:17]
	v_mfma_f32_16x16x32_bf16 v[10:13], v[148:151], v[208:211], v[10:13]
	s_setprio 0
	s_setprio 1
	v_mfma_f32_16x16x32_bf16 v[54:57], v[152:155], v[168:171], 0
	v_mfma_f32_16x16x32_bf16 v[50:53], v[160:163], v[168:171], 0
	v_mfma_f32_16x16x32_bf16 v[38:41], v[152:155], v[180:183], 0
	v_mfma_f32_16x16x32_bf16 v[34:37], v[160:163], v[180:183], 0
	v_mfma_f32_16x16x32_bf16 v[22:25], v[152:155], v[196:199], 0
	v_mfma_f32_16x16x32_bf16 v[18:21], v[160:163], v[196:199], 0
	v_mfma_f32_16x16x32_bf16 v[6:9], v[152:155], v[204:207], 0
	v_mfma_f32_16x16x32_bf16 v[2:5], v[160:163], v[204:207], 0
	v_mfma_f32_16x16x32_bf16 v[54:57], v[156:159], v[176:179], v[54:57]
	v_mfma_f32_16x16x32_bf16 v[50:53], v[164:167], v[176:179], v[50:53]
	v_mfma_f32_16x16x32_bf16 v[38:41], v[156:159], v[192:195], v[38:41]
	v_mfma_f32_16x16x32_bf16 v[34:37], v[164:167], v[192:195], v[34:37]
	v_mfma_f32_16x16x32_bf16 v[22:25], v[156:159], v[200:203], v[22:25]
	v_mfma_f32_16x16x32_bf16 v[18:21], v[164:167], v[200:203], v[18:21]
	v_mfma_f32_16x16x32_bf16 v[6:9], v[156:159], v[208:211], v[6:9]
	v_mfma_f32_16x16x32_bf16 v[2:5], v[164:167], v[208:211], v[2:5]
	s_setprio 0
	s_barrier
	s_add_i32 s55, 0, 0x18000
	s_add_i32 s56, 0, 0x1c000
	v_add_u32_e32 v148, s55, v173
	v_add_u32_e32 v164, s56, v173
	ds_read_b128 v[136:139], v148
	ds_read_b128 v[140:143], v148 offset:1024
	ds_read_b128 v[144:147], v148 offset:2048
	ds_read_b128 v[148:151], v148 offset:3072
	ds_read_b128 v[152:155], v164
	ds_read_b128 v[156:159], v164 offset:1024
	ds_read_b128 v[160:163], v164 offset:2048
	ds_read_b128 v[164:167], v164 offset:3072
	s_add_u32 s50, s78, 0xb0000
	s_addc_u32 s51, s79, 0
	s_mov_b32 m0, s80
	v_lshl_add_u64 v[214:215], s[50:51], 0, v[0:1]
	ds_read_b128 v[168:171], v175 offset:32768
	ds_read_b128 v[176:179], v175 offset:33792
	ds_read_b128 v[180:183], v175 offset:34816
	ds_read_b128 v[192:195], v175 offset:35840
	ds_read_b128 v[196:199], v175 offset:36864
	ds_read_b128 v[200:203], v175 offset:37888
	ds_read_b128 v[204:207], v175 offset:38912
	ds_read_b128 v[208:211], v175 offset:39936
	global_load_lds_dwordx4 v[214:215], off
	v_lshl_add_u64 v[214:215], s[50:51], 0, v[130:131]
	s_mov_b32 m0, s81
	s_nop 0
	global_load_lds_dwordx4 v[214:215], off
	s_waitcnt vmcnt(8)
	s_waitcnt lgkmcnt(0)
	s_barrier
	s_setprio 1
	s_waitcnt lgkmcnt(0)
	v_mfma_f32_16x16x32_bf16 v[126:129], v[136:139], v[168:171], v[126:129]
	v_mfma_f32_16x16x32_bf16 v[122:125], v[144:147], v[168:171], v[122:125]
	v_mfma_f32_16x16x32_bf16 v[110:113], v[136:139], v[180:183], v[110:113]
	v_mfma_f32_16x16x32_bf16 v[106:109], v[144:147], v[180:183], v[106:109]
	v_mfma_f32_16x16x32_bf16 v[94:97], v[136:139], v[196:199], v[94:97]
	v_mfma_f32_16x16x32_bf16 v[90:93], v[144:147], v[196:199], v[90:93]
	v_mfma_f32_16x16x32_bf16 v[78:81], v[136:139], v[204:207], v[78:81]
	v_mfma_f32_16x16x32_bf16 v[74:77], v[144:147], v[204:207], v[74:77]
	v_mfma_f32_16x16x32_bf16 v[126:129], v[140:143], v[176:179], v[126:129]
	v_mfma_f32_16x16x32_bf16 v[122:125], v[148:151], v[176:179], v[122:125]
	v_mfma_f32_16x16x32_bf16 v[110:113], v[140:143], v[192:195], v[110:113]
	v_mfma_f32_16x16x32_bf16 v[106:109], v[148:151], v[192:195], v[106:109]
	v_mfma_f32_16x16x32_bf16 v[94:97], v[140:143], v[200:203], v[94:97]
	v_mfma_f32_16x16x32_bf16 v[90:93], v[148:151], v[200:203], v[90:93]
	v_mfma_f32_16x16x32_bf16 v[78:81], v[140:143], v[208:211], v[78:81]
	v_mfma_f32_16x16x32_bf16 v[74:77], v[148:151], v[208:211], v[74:77]
	s_setprio 0
	s_setprio 1
	v_mfma_f32_16x16x32_bf16 v[118:121], v[152:155], v[168:171], v[118:121]
	v_mfma_f32_16x16x32_bf16 v[114:117], v[160:163], v[168:171], v[114:117]
	v_mfma_f32_16x16x32_bf16 v[102:105], v[152:155], v[180:183], v[102:105]
	v_mfma_f32_16x16x32_bf16 v[98:101], v[160:163], v[180:183], v[98:101]
	v_mfma_f32_16x16x32_bf16 v[86:89], v[152:155], v[196:199], v[86:89]
	v_mfma_f32_16x16x32_bf16 v[82:85], v[160:163], v[196:199], v[82:85]
	v_mfma_f32_16x16x32_bf16 v[70:73], v[152:155], v[204:207], v[70:73]
	v_mfma_f32_16x16x32_bf16 v[66:69], v[160:163], v[204:207], v[66:69]
	v_mfma_f32_16x16x32_bf16 v[118:121], v[156:159], v[176:179], v[118:121]
	v_mfma_f32_16x16x32_bf16 v[114:117], v[164:167], v[176:179], v[114:117]
	v_mfma_f32_16x16x32_bf16 v[102:105], v[156:159], v[192:195], v[102:105]
	v_mfma_f32_16x16x32_bf16 v[98:101], v[164:167], v[192:195], v[98:101]
	v_mfma_f32_16x16x32_bf16 v[86:89], v[156:159], v[200:203], v[86:89]
	v_mfma_f32_16x16x32_bf16 v[82:85], v[164:167], v[200:203], v[82:85]
	v_mfma_f32_16x16x32_bf16 v[70:73], v[156:159], v[208:211], v[70:73]
	v_mfma_f32_16x16x32_bf16 v[66:69], v[164:167], v[208:211], v[66:69]
	s_setprio 0
	s_barrier
; #define PG8_STAGE(bufoff, gbase, voff) do { _Pragma("unroll") for (int _i = 0; _i < 2; ++_i) \
;         __builtin_amdgcn_global_load_lds((const unsigned*)((const char*)(gbase) + (voff)[_i]), (PG8_LAS unsigned*)(lds + (bufoff) + ldsw + _i * 8192), 16, 0, 0); } while (0)
; #define PG8_LDA(dst, b, h) do { _Pragma("unroll") for (int m = 0; m < 4; ++m) _Pragma("unroll") for (int k = 0; k < 2; ++k) dst[m][k] = *(const PG8_LAS bf16x8*)(lds + PG8_SA(b, h) + aoff + m * 2048 + k * 1024); } while (0)
; #define PG8_MMA(ai, bj, At, Bt) do { __builtin_amdgcn_s_setprio(1); _Pragma("unroll") for (int m = 0; m < 4; ++m) _Pragma("unroll") for (int n = 0; n < 2; ++n) _Pragma("unroll") for (int k = 0; k < 2; ++k) \
;         acc[ai][bj][m][n] = __builtin_amdgcn_mfma_f32_16x16x32_bf16(Bt[n][k], At[m][k], acc[ai][bj][m][n], 0, 0, 0); __builtin_amdgcn_s_setprio(0); } while (0)
; #define PG8_WAIT_V(n) asm volatile("s_waitcnt vmcnt(" #n ")" ::: "memory")
; #define PG8_WAIT_L(n) asm volatile("s_waitcnt lgkmcnt(" #n ")" ::: "memory")
; #define PG8_BAR __builtin_amdgcn_s_barrier()
; #define PG8_SCHED __builtin_amdgcn_sched_barrier(0)
; template <class Epi, class Sched, bool ALIGN_EPI = false, bool SP2 = false>
; __device__ __forceinline__ void gemm_phase(PG8_LAS unsigned char* lds, const Gemm g, const Sched& S, const Epi& E) {
;     ...
;             PG8_LDA(At, 1, 1); PG8_STAGE(PG8_SB(1, 0), b3, voffB); PG8_STAGE(PG8_SB(1, 1), b3 + hstep, voffB); PG8_STAGE(PG8_SA(1, 0), a3, voffA);
;             PG8_WAIT_V(8); PG8_WAIT_L(0); PG8_BAR; PG8_MMA(1, 0, At, B0); PG8_MMA(1, 1, At, B1); PG8_BAR; PG8_SCHED;
	s_add_i32 s50, s55, s35
	v_lshl_add_u64 v[184:185], v[184:185], 0, s[60:61]
	s_mov_b32 m0, s50
	ds_read_b128 v[168:171], v175 offset:49152
	ds_read_b128 v[176:179], v175 offset:50176
	ds_read_b128 v[180:183], v175 offset:51200
	ds_read_b128 v[192:195], v175 offset:52224
	ds_read_b128 v[196:199], v175 offset:53248
	ds_read_b128 v[200:203], v175 offset:54272
	ds_read_b128 v[204:207], v175 offset:55296
	ds_read_b128 v[208:211], v175 offset:56320
	global_load_lds_dwordx4 v[184:185], off
	s_add_i32 m0, s50, 0x2000
	s_add_u32 s50, s76, 0xb0080
	v_lshl_add_u64 v[184:185], v[188:189], 0, s[60:61]
	s_addc_u32 s51, s77, 0
	s_add_i32 s55, s56, s35
	global_load_lds_dwordx4 v[184:185], off
	v_lshl_add_u64 v[184:185], s[50:51], 0, v[0:1]
	s_mov_b32 m0, s55
	s_nop 0
	global_load_lds_dwordx4 v[184:185], off
	v_lshl_add_u64 v[184:185], s[50:51], 0, v[130:131]
	s_add_i32 m0, s55, 0x2000
	s_nop 0
	global_load_lds_dwordx4 v[184:185], off
	v_lshl_add_u64 v[184:185], v[190:191], 0, s[60:61]
	s_mov_b32 m0, s83
	s_nop 0
	global_load_lds_dwordx4 v[184:185], off
	v_lshl_add_u64 v[184:185], v[212:213], 0, s[60:61]
	s_mov_b32 m0, s84
	s_nop 0
	global_load_lds_dwordx4 v[184:185], off
	s_waitcnt vmcnt(8)
	s_waitcnt lgkmcnt(0)
	s_barrier
	s_setprio 1
	s_waitcnt lgkmcnt(0)
	v_mfma_f32_16x16x32_bf16 v[62:65], v[136:139], v[168:171], v[62:65]
	v_mfma_f32_16x16x32_bf16 v[58:61], v[144:147], v[168:171], v[58:61]
	v_mfma_f32_16x16x32_bf16 v[46:49], v[136:139], v[180:183], v[46:49]
	v_mfma_f32_16x16x32_bf16 v[42:45], v[144:147], v[180:183], v[42:45]
	v_mfma_f32_16x16x32_bf16 v[30:33], v[136:139], v[196:199], v[30:33]
	v_mfma_f32_16x16x32_bf16 v[26:29], v[144:147], v[196:199], v[26:29]
	v_mfma_f32_16x16x32_bf16 v[14:17], v[136:139], v[204:207], v[14:17]
	v_mfma_f32_16x16x32_bf16 v[10:13], v[144:147], v[204:207], v[10:13]
	v_mfma_f32_16x16x32_bf16 v[62:65], v[140:143], v[176:179], v[62:65]
	v_mfma_f32_16x16x32_bf16 v[58:61], v[148:151], v[176:179], v[58:61]
	v_mfma_f32_16x16x32_bf16 v[46:49], v[140:143], v[192:195], v[46:49]
	v_mfma_f32_16x16x32_bf16 v[42:45], v[148:151], v[192:195], v[42:45]
	v_mfma_f32_16x16x32_bf16 v[30:33], v[140:143], v[200:203], v[30:33]
	v_mfma_f32_16x16x32_bf16 v[26:29], v[148:151], v[200:203], v[26:29]
	v_mfma_f32_16x16x32_bf16 v[14:17], v[140:143], v[208:211], v[14:17]
	v_mfma_f32_16x16x32_bf16 v[10:13], v[148:151], v[208:211], v[10:13]
	s_setprio 0
	s_setprio 1
	v_mfma_f32_16x16x32_bf16 v[54:57], v[152:155], v[168:171], v[54:57]
	v_mfma_f32_16x16x32_bf16 v[50:53], v[160:163], v[168:171], v[50:53]
	v_mfma_f32_16x16x32_bf16 v[38:41], v[152:155], v[180:183], v[38:41]
	v_mfma_f32_16x16x32_bf16 v[34:37], v[160:163], v[180:183], v[34:37]
	v_mfma_f32_16x16x32_bf16 v[22:25], v[152:155], v[196:199], v[22:25]
	v_mfma_f32_16x16x32_bf16 v[18:21], v[160:163], v[196:199], v[18:21]
	v_mfma_f32_16x16x32_bf16 v[6:9], v[152:155], v[204:207], v[6:9]
	v_mfma_f32_16x16x32_bf16 v[2:5], v[160:163], v[204:207], v[2:5]
	v_mfma_f32_16x16x32_bf16 v[54:57], v[156:159], v[176:179], v[54:57]
	v_mfma_f32_16x16x32_bf16 v[50:53], v[164:167], v[176:179], v[50:53]
	v_mfma_f32_16x16x32_bf16 v[38:41], v[156:159], v[192:195], v[38:41]
	v_mfma_f32_16x16x32_bf16 v[34:37], v[164:167], v[192:195], v[34:37]
	v_mfma_f32_16x16x32_bf16 v[22:25], v[156:159], v[200:203], v[22:25]
	v_mfma_f32_16x16x32_bf16 v[18:21], v[164:167], v[200:203], v[18:21]
	v_mfma_f32_16x16x32_bf16 v[6:9], v[156:159], v[208:211], v[6:9]
	v_mfma_f32_16x16x32_bf16 v[2:5], v[164:167], v[208:211], v[2:5]
	s_setprio 0
	s_barrier
	s_add_i32 s54, s54, 2
	s_add_u32 s52, s52, 0x100
	s_addc_u32 s53, s53, 0
	s_cmp_gt_u32 s54, 41
	s_mov_b64 s[72:73], s[74:75]
	s_cbranch_scc0 .LBB0_1512
